# SwiGLU: log2e folded into gate weights and ln2 into up weights at the f32->bf16 transposes; epilogue drops one v_mul per element (exp2 with neg modifier on the accumulator)
# speedup vs baseline: 1.0117x; 1.0027x over previous
; #define LAS __attribute__((address_space(3)))
; __device__ __forceinline__ unsigned pk2(float lo, float hi) { return f2bf(lo) | (f2bf(hi) << 16); }
; __device__ __forceinline__ void transpose_item(const float* W, int ldw, int k0, int nsrc0, bf16_t* WT, int ldt, int drow0, int dk0, LAS float* scr, int lane) {
; #pragma unroll
;     for (int i = 0; i < 8; ++i) { const int kk = 8 * i + (lane >> 3), c4 = lane & 7; const f32x4 v = __builtin_nontemporal_load((const f32x4*)(W + (size_t)(k0 + kk) * ldw + nsrc0 + 4 * c4));
;         scr[kk * 33 + 4 * c4] = v[0]; scr[kk * 33 + 4 * c4 + 1] = v[1]; scr[kk * 33 + 4 * c4 + 2] = v[2]; scr[kk * 33 + 4 * c4 + 3] = v[3]; }
;     asm volatile("s_waitcnt lgkmcnt(0)" ::: "memory");
;     const int c = lane & 7;
; #pragma unroll
;     for (int j = 0; j < 4; ++j) { const int n = (lane >> 3) + 8 * j; const LAS float* s = scr + (8 * c) * 33 + n;
;         u32x4 o; o.x = pk2(s[0 * 33], s[1 * 33]); o.y = pk2(s[2 * 33], s[3 * 33]); o.z = pk2(s[4 * 33], s[5 * 33]); o.w = pk2(s[6 * 33], s[7 * 33]);
;         *(u32x4*)(WT + (size_t)(drow0 + n) * ldt + dk0 + k0 + 8 * c) = o; }
;     asm volatile("s_waitcnt lgkmcnt(0)" ::: "memory");
; }
; __device__ __forceinline__ void weight_transposes(const Args& A, LAS unsigned char* lds, int wk, int nwk, const int tid, const int stage) {
;     const int lane = tid & 63, wave = __builtin_amdgcn_readfirstlane(tid >> 6);
;     unsigned char* ws = A.ws;
;     LAS float* scr = (LAS float*)(lds + wave * 16384);
;     const int gw = wk * 8 + wave, NGW = nwk * 8;
;     constexpr int I_GU = 16 * 88, I_DN = 44 * 32, I_IN = 16 * 72, I_OUT = 12 * 32;
;     const bool ffn2 = stage >= 2;
;     const int n_gu = (stage == 0 || stage == 2) ? 2 * I_GU : 0, n_dn = (stage == 1 || stage == 3) ? I_DN : 0, n_x = stage == 1 ? I_IN : (stage == 4 ? I_OUT : 0);
;     const int nit = n_gu + n_dn + n_x;
;     for (int it = gw; it < nit; it += NGW) {
;         int r = it;
;         if (r < n_gu) {
;             const int up = r / I_GU; r -= up * I_GU; const int kb = r / 88, nb = r % 88, n0 = nb * 32;
;             const float* W = A.in[ffn2 ? (up ? I_F2U : I_F2G) : (up ? I_F1U : I_F1G)];
;             bf16_t* WT = (bf16_t*)(ws + (ffn2 ? WS_WGU2 : WS_WGU1));
;             transpose_item(W, DFF, kb * 64, n0, WT, DM, 256 * (n0 >> 7) + (n0 & 127) + (up ? 128 : 0), 0, scr, lane);
.LBB0_184:
	s_mul_hi_i32 s0, s4, 0x2e8ba2e9
	s_lshr_b32 s2, s0, 31
	s_ashr_i32 s0, s0, 8
	s_add_i32 s0, s0, s2
	s_mulk_i32 s0, 0x580
	s_sub_i32 s0, s4, s0
	s_sext_i32_i16 s2, s0
	s_mulk_i32 s2, 0xba3
	s_lshr_b32 s3, s2, 31
	s_ashr_i32 s2, s2, 18
	s_add_i32 s2, s2, s3
	s_sext_i32_i16 s3, s2
	s_mulk_i32 s2, 0x58
	s_sub_i32 s2, s0, s2
	s_lshl_b32 s0, s3, 6
	s_sext_i32_i16 s3, s2
	s_lshl_b32 s2, s3, 5
	s_lshl_b32 s3, s3, 6
	s_add_i32 s1, s4, 0x57f
	s_and_b32 s7, s3, 0xffffff00
	s_and_b32 s8, s2, 0x60
	s_mov_b32 s98, 0x3f317218
	s_cmpk_lt_u32 s1, 0xaff
	s_cselect_b32 s10, 0, 0x80
	s_cselect_b32 s98, 0x3fb8aa3b, s98
	s_cselect_b32 s1, s91, s13
	s_cselect_b32 s9, s90, s12
	s_ashr_i32 s3, s2, 31
	s_or_b32 s8, s8, s10
	s_lshl_b64 s[2:3], s[2:3], 2
	s_or_b32 s7, s8, s7
	v_or_b32_e32 v28, s0, v4
	v_or_b32_e32 v29, s0, v5
	v_or_b32_e32 v31, s0, v6
	s_add_u32 s2, s9, s2
	v_or_b32_e32 v33, s0, v7
	v_or_b32_e32 v35, s0, v8
	v_or_b32_e32 v37, s0, v9
	v_or_b32_e32 v39, s0, v10
	v_or_b32_e32 v41, s0, v11
	v_mul_i32_i24_e32 v28, 0xb00, v28
	v_mul_i32_i24_e32 v30, 0xb00, v29
	v_mul_i32_i24_e32 v32, 0xb00, v31
	v_or_b32_e32 v44, s7, v4
	v_or_b32_e32 v46, s7, v5
	v_or_b32_e32 v48, s7, v6
	v_or_b32_e32 v50, s7, v7
	s_addc_u32 s3, s1, s3
	v_mul_i32_i24_e32 v34, 0xb00, v33
	v_mul_i32_i24_e32 v36, 0xb00, v35
	v_mul_i32_i24_e32 v38, 0xb00, v37
	v_mul_i32_i24_e32 v40, 0xb00, v39
	v_mul_i32_i24_e32 v42, 0xb00, v41
	v_ashrrev_i32_e32 v29, 31, v28
	v_ashrrev_i32_e32 v31, 31, v30
	v_ashrrev_i32_e32 v33, 31, v32
	s_ashr_i32 s1, s0, 31
	v_ashrrev_i32_e32 v45, 31, v44
	v_ashrrev_i32_e32 v47, 31, v46
	v_ashrrev_i32_e32 v49, 31, v48
	v_ashrrev_i32_e32 v51, 31, v50
	v_lshl_add_u64 v[52:53], s[2:3], 0, v[0:1]
	v_ashrrev_i32_e32 v35, 31, v34
	v_ashrrev_i32_e32 v37, 31, v36
	v_ashrrev_i32_e32 v39, 31, v38
	v_ashrrev_i32_e32 v41, 31, v40
	v_ashrrev_i32_e32 v43, 31, v42
	v_lshl_add_u64 v[54:55], s[0:1], 1, v[2:3]
	v_lshlrev_b64 v[44:45], 11, v[44:45]
	v_lshlrev_b64 v[46:47], 11, v[46:47]
	v_lshlrev_b64 v[48:49], 11, v[48:49]
	v_lshlrev_b64 v[50:51], 11, v[50:51]
	v_lshl_add_u64 v[28:29], v[28:29], 2, v[52:53]
	v_lshl_add_u64 v[56:57], v[30:31], 2, v[52:53]
	v_lshl_add_u64 v[58:59], v[32:33], 2, v[52:53]
	v_lshl_add_u64 v[60:61], v[34:35], 2, v[52:53]
	v_lshl_add_u64 v[62:63], v[36:37], 2, v[52:53]
	v_lshl_add_u64 v[64:65], v[38:39], 2, v[52:53]
	v_lshl_add_u64 v[66:67], v[40:41], 2, v[52:53]
	v_lshl_add_u64 v[68:69], v[42:43], 2, v[52:53]
	v_lshl_add_u64 v[70:71], v[54:55], 0, v[44:45]
	v_lshl_add_u64 v[72:73], v[54:55], 0, v[46:47]
	v_lshl_add_u64 v[74:75], v[54:55], 0, v[48:49]
	v_lshl_add_u64 v[76:77], v[54:55], 0, v[50:51]
	global_load_dwordx4 v[28:31], v[28:29], off nt
	s_nop 0
	global_load_dwordx4 v[32:35], v[56:57], off nt
	global_load_dwordx4 v[36:39], v[58:59], off nt
	global_load_dwordx4 v[40:43], v[60:61], off nt
	global_load_dwordx4 v[44:47], v[62:63], off nt
	global_load_dwordx4 v[48:51], v[64:65], off nt
	global_load_dwordx4 v[52:55], v[66:67], off nt
	s_nop 0
	global_load_dwordx4 v[56:59], v[68:69], off nt
	s_add_i32 s4, s4, s96
	s_cmpk_gt_i32 s4, 0xaff
	s_waitcnt vmcnt(7)
	v_mul_f32_e32 v28, s98, v28
	v_mul_f32_e32 v29, s98, v29
	v_mul_f32_e32 v30, s98, v30
	v_mul_f32_e32 v31, s98, v31
	ds_write2_b32 v13, v28, v29 offset1:1
	ds_write2_b32 v13, v30, v31 offset0:2 offset1:3
	s_waitcnt vmcnt(6)
	v_mul_f32_e32 v32, s98, v32
	v_mul_f32_e32 v33, s98, v33
	v_mul_f32_e32 v34, s98, v34
	v_mul_f32_e32 v35, s98, v35
	ds_write2_b32 v14, v32, v33 offset1:1
	ds_write2_b32 v15, v34, v35 offset1:1
	s_waitcnt vmcnt(5)
	v_mul_f32_e32 v36, s98, v36
	v_mul_f32_e32 v37, s98, v37
	v_mul_f32_e32 v38, s98, v38
	v_mul_f32_e32 v39, s98, v39
	ds_write2_b32 v16, v36, v37 offset1:1
	ds_write2_b32 v17, v38, v39 offset1:1
	s_waitcnt vmcnt(4)
	v_mul_f32_e32 v40, s98, v40
	v_mul_f32_e32 v41, s98, v41
	v_mul_f32_e32 v42, s98, v42
	v_mul_f32_e32 v43, s98, v43
	ds_write2_b32 v18, v40, v41 offset1:1
	ds_write2_b32 v19, v42, v43 offset1:1
	s_waitcnt vmcnt(3)
	v_mul_f32_e32 v44, s98, v44
	v_mul_f32_e32 v45, s98, v45
	v_mul_f32_e32 v46, s98, v46
	v_mul_f32_e32 v47, s98, v47
	ds_write2_b32 v20, v44, v45 offset1:1
	ds_write2_b32 v21, v46, v47 offset1:1
	s_waitcnt vmcnt(2)
	v_mul_f32_e32 v48, s98, v48
	v_mul_f32_e32 v49, s98, v49
	v_mul_f32_e32 v50, s98, v50
	v_mul_f32_e32 v51, s98, v51
	ds_write2_b32 v22, v48, v49 offset1:1
	ds_write2_b32 v23, v50, v51 offset1:1
	s_waitcnt vmcnt(1)
	v_mul_f32_e32 v52, s98, v52
	v_mul_f32_e32 v53, s98, v53
	v_mul_f32_e32 v54, s98, v54
	v_mul_f32_e32 v55, s98, v55
	ds_write2_b32 v24, v52, v53 offset1:1
	ds_write2_b32 v25, v54, v55 offset1:1
	s_waitcnt vmcnt(0)
; #define LAS __attribute__((address_space(3)))
; __device__ __forceinline__ unsigned pk2(float lo, float hi) { return f2bf(lo) | (f2bf(hi) << 16); }
; __device__ __forceinline__ void transpose_item(const float* W, int ldw, int k0, int nsrc0, bf16_t* WT, int ldt, int drow0, int dk0, LAS float* scr, int lane) {
;     ...
;     for (int i = 0; i < 8; ++i) { const int kk = 8 * i + (lane >> 3), c4 = lane & 7; const f32x4 v = __builtin_nontemporal_load((const f32x4*)(W + (size_t)(k0 + kk) * ldw + nsrc0 + 4 * c4));
;         scr[kk * 33 + 4 * c4] = v[0]; scr[kk * 33 + 4 * c4 + 1] = v[1]; scr[kk * 33 + 4 * c4 + 2] = v[2]; scr[kk * 33 + 4 * c4 + 3] = v[3]; }
;     asm volatile("s_waitcnt lgkmcnt(0)" ::: "memory");
;     const int c = lane & 7;
; #pragma unroll
;     for (int j = 0; j < 4; ++j) { const int n = (lane >> 3) + 8 * j; const LAS float* s = scr + (8 * c) * 33 + n;
;         u32x4 o; o.x = pk2(s[0 * 33], s[1 * 33]); o.y = pk2(s[2 * 33], s[3 * 33]); o.z = pk2(s[4 * 33], s[5 * 33]); o.w = pk2(s[6 * 33], s[7 * 33]);
;         *(u32x4*)(WT + (size_t)(drow0 + n) * ldt + dk0 + k0 + 8 * c) = o; }
;     asm volatile("s_waitcnt lgkmcnt(0)" ::: "memory");
	v_mul_f32_e32 v56, s98, v56
	v_mul_f32_e32 v57, s98, v57
	v_mul_f32_e32 v58, s98, v58
	v_mul_f32_e32 v59, s98, v59
	ds_write2_b32 v26, v56, v57 offset1:1
	ds_write2_b32 v27, v58, v59 offset1:1
	s_waitcnt lgkmcnt(0)
	ds_read2_b32 v[28:29], v12 offset0:33 offset1:41
	ds_read2_b32 v[30:31], v12 offset1:8
	ds_read2_b32 v[32:33], v12 offset0:66 offset1:74
	ds_read2_b32 v[34:35], v12 offset0:99 offset1:107
	ds_read2_b32 v[36:37], v12 offset0:132 offset1:140
	ds_read2_b32 v[38:39], v12 offset0:165 offset1:173
	ds_read2_b32 v[40:41], v12 offset0:198 offset1:206
	ds_read2_b32 v[42:43], v12 offset0:231 offset1:239
	ds_read2_b32 v[44:45], v12 offset0:49 offset1:57
	ds_read2_b32 v[46:47], v12 offset0:16 offset1:24
	ds_read2_b32 v[48:49], v12 offset0:82 offset1:90
	ds_read2_b32 v[50:51], v12 offset0:115 offset1:123
	ds_read2_b32 v[52:53], v12 offset0:148 offset1:156
	ds_read2_b32 v[54:55], v12 offset0:181 offset1:189
	ds_read2_b32 v[56:57], v12 offset0:214 offset1:222
	ds_read2_b32 v[58:59], v12 offset0:247 offset1:255
	s_waitcnt lgkmcnt(14)
	v_bfe_u32 v60, v30, 16, 1
	s_waitcnt lgkmcnt(13)
	v_bfe_u32 v62, v32, 16, 1
	s_waitcnt lgkmcnt(12)
	v_bfe_u32 v63, v34, 16, 1
	s_waitcnt lgkmcnt(11)
	v_bfe_u32 v64, v36, 16, 1
	s_waitcnt lgkmcnt(10)
	v_bfe_u32 v65, v38, 16, 1
	s_waitcnt lgkmcnt(9)
	v_bfe_u32 v66, v40, 16, 1
	v_bfe_u32 v69, v29, 16, 1
	v_bfe_u32 v78, v33, 16, 1
	v_bfe_u32 v79, v35, 16, 1
	v_bfe_u32 v80, v37, 16, 1
	v_bfe_u32 v81, v39, 16, 1
	v_bfe_u32 v61, v28, 16, 1
	v_bfe_u32 v67, v31, 16, 1
	s_waitcnt lgkmcnt(8)
	v_bfe_u32 v68, v42, 16, 1
	v_bfe_u32 v82, v41, 16, 1
	v_bfe_u32 v83, v43, 16, 1
	s_waitcnt lgkmcnt(6)
	v_bfe_u32 v84, v46, 16, 1
	s_waitcnt lgkmcnt(5)
	v_bfe_u32 v86, v48, 16, 1
	s_waitcnt lgkmcnt(4)
	v_bfe_u32 v87, v50, 16, 1
	s_waitcnt lgkmcnt(3)
	v_bfe_u32 v88, v52, 16, 1
	s_waitcnt lgkmcnt(2)
	v_bfe_u32 v89, v54, 16, 1
	s_waitcnt lgkmcnt(1)
	v_bfe_u32 v90, v56, 16, 1
	v_bfe_u32 v91, v47, 16, 1
	v_bfe_u32 v94, v49, 16, 1
	v_bfe_u32 v95, v51, 16, 1
	v_bfe_u32 v96, v53, 16, 1
	v_bfe_u32 v98, v57, 16, 1
	v_add3_u32 v30, v30, v60, s5
	v_add3_u32 v60, v29, v69, s5
	v_add3_u32 v29, v32, v62, s5
	v_add3_u32 v32, v33, v78, s5
	v_add3_u32 v33, v34, v63, s5
	v_add3_u32 v34, v35, v79, s5
	v_add3_u32 v35, v36, v64, s5
	v_add3_u32 v36, v37, v80, s5
	v_add3_u32 v37, v38, v65, s5
	v_add3_u32 v38, v39, v81, s5
	v_add3_u32 v39, v40, v66, s5
	v_bfe_u32 v85, v44, 16, 1
	s_waitcnt lgkmcnt(0)
	v_bfe_u32 v92, v58, 16, 1
	v_bfe_u32 v93, v45, 16, 1
	v_bfe_u32 v97, v55, 16, 1
	v_bfe_u32 v99, v59, 16, 1
	v_add3_u32 v31, v31, v67, s5
	v_add3_u32 v28, v28, v61, s5
	v_add3_u32 v40, v41, v82, s5
	v_add3_u32 v41, v42, v68, s5
	v_add3_u32 v42, v43, v83, s5
	v_add3_u32 v43, v46, v84, s5
	v_add3_u32 v46, v47, v91, s5
	v_add3_u32 v47, v48, v86, s5
	v_add3_u32 v48, v49, v94, s5
	v_add3_u32 v49, v50, v87, s5
	v_add3_u32 v50, v51, v95, s5
	v_add3_u32 v51, v52, v88, s5
	v_add3_u32 v52, v54, v89, s5
	v_add3_u32 v54, v56, v90, s5
	v_add3_u32 v53, v53, v96, s5
	v_add3_u32 v57, v57, v98, s5
	v_lshrrev_b32_e32 v30, 16, v30
	v_lshrrev_b32_e32 v29, 16, v29
	v_lshrrev_b32_e32 v35, 16, v35
	v_lshrrev_b32_e32 v39, 16, v39
	v_add3_u32 v44, v44, v85, s5
	v_add3_u32 v45, v45, v93, s5
	v_add3_u32 v56, v58, v92, s5
	v_add3_u32 v55, v55, v97, s5
	v_add3_u32 v58, v59, v99, s5
	v_lshrrev_b32_e32 v59, 16, v31
	v_lshrrev_b32_e32 v61, 16, v32
	v_lshrrev_b32_e32 v36, 16, v36
	v_lshrrev_b32_e32 v40, 16, v40
	v_lshrrev_b32_e32 v43, 16, v43
	v_lshrrev_b32_e32 v47, 16, v47
	v_lshrrev_b32_e32 v51, 16, v51
	v_lshrrev_b32_e32 v54, 16, v54
	v_lshrrev_b32_e32 v46, 16, v46
	v_lshrrev_b32_e32 v48, 16, v48
	v_lshrrev_b32_e32 v53, 16, v53
	v_lshrrev_b32_e32 v57, 16, v57
	v_and_or_b32 v28, v28, s6, v30
	v_and_or_b32 v29, v33, s6, v29
	v_and_or_b32 v30, v37, s6, v35
	v_and_or_b32 v31, v41, s6, v39
	v_and_or_b32 v32, v60, s6, v59
	v_and_or_b32 v33, v34, s6, v61
	v_and_or_b32 v34, v38, s6, v36
	v_and_or_b32 v35, v42, s6, v40
	v_and_or_b32 v36, v44, s6, v43
	v_and_or_b32 v37, v49, s6, v47
	v_and_or_b32 v38, v52, s6, v51
	v_and_or_b32 v39, v56, s6, v54
	v_and_or_b32 v40, v45, s6, v46
	v_and_or_b32 v41, v50, s6, v48
	v_and_or_b32 v42, v55, s6, v53
	v_and_or_b32 v43, v58, s6, v57
	global_store_dwordx4 v[70:71], v[28:31], off
	global_store_dwordx4 v[72:73], v[32:35], off
	global_store_dwordx4 v[74:75], v[36:39], off
	global_store_dwordx4 v[76:77], v[40:43], off
	s_waitcnt lgkmcnt(0)
	s_cbranch_scc0 .LBB0_184

; __device__ __forceinline__ unsigned cvt_pk_bf16(float lo, float hi) { unsigned r; asm volatile("v_cvt_pk_bf16_f32 %0, %1, %2" : "=v"(r) : "v"(lo), "v"(hi)); return r; }
; __device__ __forceinline__ float silu_f(float g) { return g * __builtin_amdgcn_rcpf(1.0f + __builtin_amdgcn_exp2f(-1.4426950408889634f * g)); }
;     __device__ __forceinline__ void operator()(const f32x4 (&acc)[2][2][4][2], const Unit& u, int wr, int wc, int fr, int fq) const {
;         const int row0 = u.pm * BM + wr * 64 + fr, col0 = u.pn * 128 + wc * 32 + 8 * fq;
; #pragma unroll
;         for (int ai = 0; ai < 2; ++ai)
; #pragma unroll
;             for (int m = 0; m < 4; ++m) {
;                 bf16_t* rowp = H + (size_t)(row0 + ai * HALF + m * 16) * DFF + col0;
;                 const f32x4 g0 = acc[ai][0][m][0], g1 = acc[ai][0][m][1], u0 = acc[ai][1][m][0], u1 = acc[ai][1][m][1];
;                 u32x4 w;
;                 w.x = cvt_pk_bf16(silu_f(g0[0]) * u0[0], silu_f(g0[1]) * u0[1]); w.y = cvt_pk_bf16(silu_f(g0[2]) * u0[2], silu_f(g0[3]) * u0[3]);
;                 w.z = cvt_pk_bf16(silu_f(g1[0]) * u1[0], silu_f(g1[1]) * u1[1]); w.w = cvt_pk_bf16(silu_f(g1[2]) * u1[2], silu_f(g1[3]) * u1[3]);
;                 *(u32x4*)rowp = w;
;             }
;     }
.LBB0_327:
	v_exp_f32_e64 v154, -v125
	v_lshl_or_b32 v144, s42, 7, v148
	v_lshl_add_u32 v150, s6, 8, v146
	v_ashrrev_i32_e32 v145, 31, v144
	v_add_f32_e32 v154, 1.0, v154
	v_rcp_f32_e32 v154, v154
	v_mov_b64_e32 v[142:143], s[16:17]
	v_mad_i64_i32 v[152:153], s[2:3], v150, s47, v[142:143]
	v_exp_f32_e64 v151, -v124
	v_lshlrev_b64 v[144:145], 1, v[144:145]
	v_lshl_add_u64 v[156:157], v[152:153], 0, v[144:145]
	v_mul_f32_e32 v152, v125, v154
	v_exp_f32_e64 v153, -v126
	v_exp_f32_e64 v154, -v127
	v_add_f32_e32 v151, 1.0, v151
	v_rcp_f32_e32 v151, v151
	v_add_f32_e32 v153, 1.0, v153
	v_add_f32_e32 v154, 1.0, v154
	v_rcp_f32_e32 v153, v153
	v_rcp_f32_e32 v154, v154
	v_mul_f32_e32 v151, v124, v151
	v_mul_f32_e32 v151, v151, v92
	v_mul_f32_e32 v152, v152, v93
	v_cvt_pk_bf16_f32 v152, v151, v152
	v_mul_f32_e32 v151, v126, v153
	v_mul_f32_e32 v153, v127, v154
	v_exp_f32_e64 v154, -v120
	v_exp_f32_e64 v155, -v121
	v_mul_f32_e32 v151, v151, v94
	v_mul_f32_e32 v153, v153, v95
	v_add_f32_e32 v154, 1.0, v154
	v_add_f32_e32 v155, 1.0, v155
	v_rcp_f32_e32 v154, v154
	v_rcp_f32_e32 v155, v155
	v_cvt_pk_bf16_f32 v153, v151, v153
	v_mul_f32_e32 v151, v120, v154
	v_mul_f32_e32 v154, v121, v155
	v_exp_f32_e64 v155, -v122
	v_exp_f32_e64 v158, -v123
	v_mul_f32_e32 v151, v151, v88
	v_mul_f32_e32 v154, v154, v89
	v_add_f32_e32 v155, 1.0, v155
	v_add_f32_e32 v158, 1.0, v158
	v_rcp_f32_e32 v155, v155
	v_rcp_f32_e32 v158, v158
	v_cvt_pk_bf16_f32 v154, v151, v154
	s_add_u32 s34, s25, 0xffffff00
	v_mul_f32_e32 v151, v122, v155
	v_mul_f32_e32 v155, v123, v158
	v_mul_f32_e32 v155, v155, v91
	v_mul_f32_e32 v151, v151, v90
	v_cvt_pk_bf16_f32 v155, v151, v155
	global_store_dwordx4 v[156:157], v[152:155], off
	v_or_b32_e32 v151, 16, v150
	v_exp_f32_e64 v154, -v116
	v_exp_f32_e64 v155, -v117
	v_mad_i64_i32 v[152:153], s[2:3], v151, s47, v[142:143]
	v_add_f32_e32 v151, 1.0, v154
	v_add_f32_e32 v154, 1.0, v155
	v_rcp_f32_e32 v154, v154
	v_lshl_add_u64 v[156:157], v[152:153], 0, v[144:145]
	v_exp_f32_e64 v153, -v118
	v_mul_f32_e32 v152, v117, v154
	v_exp_f32_e64 v154, -v119
	v_rcp_f32_e32 v151, v151
	v_add_f32_e32 v153, 1.0, v153
	v_rcp_f32_e32 v153, v153
	v_add_f32_e32 v154, 1.0, v154
	v_rcp_f32_e32 v154, v154
	v_mul_f32_e32 v151, v116, v151
	v_mul_f32_e32 v151, v151, v84
	v_mul_f32_e32 v152, v152, v85
	v_cvt_pk_bf16_f32 v152, v151, v152
	v_mul_f32_e32 v151, v118, v153
	v_mul_f32_e32 v153, v119, v154
	v_exp_f32_e64 v154, -v112
	v_exp_f32_e64 v155, -v113
	v_mul_f32_e32 v151, v151, v86
	v_mul_f32_e32 v153, v153, v87
	v_add_f32_e32 v154, 1.0, v154
	v_add_f32_e32 v155, 1.0, v155
	v_rcp_f32_e32 v154, v154
	v_rcp_f32_e32 v155, v155
	v_cvt_pk_bf16_f32 v153, v151, v153
	v_exp_f32_e64 v158, -v115
	v_mul_f32_e32 v151, v112, v154
	v_mul_f32_e32 v154, v113, v155
	v_exp_f32_e64 v155, -v114
	v_add_f32_e32 v158, 1.0, v158
	v_rcp_f32_e32 v158, v158
	v_mul_f32_e32 v151, v151, v80
	v_add_f32_e32 v155, 1.0, v155
	v_rcp_f32_e32 v155, v155
	v_mul_f32_e32 v154, v154, v81
	v_cvt_pk_bf16_f32 v154, v151, v154
	s_addc_u32 s35, s51, -1
	v_mul_f32_e32 v151, v114, v155
	v_mul_f32_e32 v155, v115, v158
	v_mul_f32_e32 v155, v155, v83
	v_mul_f32_e32 v151, v151, v82
	v_cvt_pk_bf16_f32 v155, v151, v155
	global_store_dwordx4 v[156:157], v[152:155], off
	v_or_b32_e32 v151, 32, v150
	v_exp_f32_e64 v154, -v108
	v_exp_f32_e64 v155, -v109
	v_mad_i64_i32 v[152:153], s[2:3], v151, s47, v[142:143]
	v_add_f32_e32 v151, 1.0, v154
	v_add_f32_e32 v154, 1.0, v155
	v_rcp_f32_e32 v154, v154
	v_lshl_add_u64 v[156:157], v[152:153], 0, v[144:145]
	v_exp_f32_e64 v153, -v110
	v_mul_f32_e32 v152, v109, v154
	v_exp_f32_e64 v154, -v111
	v_rcp_f32_e32 v151, v151
	v_add_f32_e32 v153, 1.0, v153
	v_rcp_f32_e32 v153, v153
	v_add_f32_e32 v154, 1.0, v154
	v_rcp_f32_e32 v154, v154
	v_mul_f32_e32 v151, v108, v151
	v_mul_f32_e32 v151, v151, v76
	v_mul_f32_e32 v152, v152, v77
	v_cvt_pk_bf16_f32 v152, v151, v152
	v_mul_f32_e32 v151, v110, v153
	v_mul_f32_e32 v153, v111, v154
	v_exp_f32_e64 v154, -v104
	v_exp_f32_e64 v155, -v105
	v_mul_f32_e32 v151, v151, v78
	v_mul_f32_e32 v153, v153, v79
	v_add_f32_e32 v154, 1.0, v154
	v_add_f32_e32 v155, 1.0, v155
	v_rcp_f32_e32 v154, v154
	v_rcp_f32_e32 v155, v155
	v_cvt_pk_bf16_f32 v153, v151, v153
	v_exp_f32_e64 v158, -v107
	v_mul_f32_e32 v151, v104, v154
	v_mul_f32_e32 v154, v105, v155
	v_exp_f32_e64 v155, -v106
	v_add_f32_e32 v158, 1.0, v158
	v_rcp_f32_e32 v158, v158
	v_mul_f32_e32 v151, v151, v72
	v_add_f32_e32 v155, 1.0, v155
	v_rcp_f32_e32 v155, v155
	v_mul_f32_e32 v154, v154, v73
	v_cvt_pk_bf16_f32 v154, v151, v154
	s_andn2_b64 vcc, exec, s[36:37]
	v_mul_f32_e32 v151, v106, v155
	v_mul_f32_e32 v155, v107, v158
	v_mul_f32_e32 v155, v155, v75
	v_mul_f32_e32 v151, v151, v74
	v_cvt_pk_bf16_f32 v155, v151, v155
	global_store_dwordx4 v[156:157], v[152:155], off
	v_or_b32_e32 v151, 48, v150
	v_exp_f32_e64 v154, -v100
	v_exp_f32_e64 v155, -v101
	v_mad_i64_i32 v[152:153], s[2:3], v151, s47, v[142:143]
	v_add_f32_e32 v151, 1.0, v154
	v_add_f32_e32 v154, 1.0, v155
	v_rcp_f32_e32 v154, v154
	v_lshl_add_u64 v[156:157], v[152:153], 0, v[144:145]
	v_exp_f32_e64 v153, -v102
	v_mul_f32_e32 v152, v101, v154
	v_exp_f32_e64 v154, -v103
	v_rcp_f32_e32 v151, v151
	v_add_f32_e32 v153, 1.0, v153
	v_rcp_f32_e32 v153, v153
	v_add_f32_e32 v154, 1.0, v154
	v_rcp_f32_e32 v154, v154
	v_mul_f32_e32 v151, v100, v151
	v_mul_f32_e32 v151, v151, v68
	v_mul_f32_e32 v152, v152, v69
	v_cvt_pk_bf16_f32 v152, v151, v152
	v_mul_f32_e32 v151, v102, v153
	v_mul_f32_e32 v153, v103, v154
	v_exp_f32_e64 v154, -v96
	v_exp_f32_e64 v155, -v97
	v_mul_f32_e32 v151, v151, v70
	v_mul_f32_e32 v153, v153, v71
	v_add_f32_e32 v154, 1.0, v154
; __device__ __forceinline__ unsigned cvt_pk_bf16(float lo, float hi) { unsigned r; asm volatile("v_cvt_pk_bf16_f32 %0, %1, %2" : "=v"(r) : "v"(lo), "v"(hi)); return r; }
; __device__ __forceinline__ float silu_f(float g) { return g * __builtin_amdgcn_rcpf(1.0f + __builtin_amdgcn_exp2f(-1.4426950408889634f * g)); }
;     __device__ __forceinline__ void operator()(const f32x4 (&acc)[2][2][4][2], const Unit& u, int wr, int wc, int fr, int fq) const {
;         const int row0 = u.pm * BM + wr * 64 + fr, col0 = u.pn * 128 + wc * 32 + 8 * fq;
; #pragma unroll
;         for (int ai = 0; ai < 2; ++ai)
; #pragma unroll
;             for (int m = 0; m < 4; ++m) {
;                 bf16_t* rowp = H + (size_t)(row0 + ai * HALF + m * 16) * DFF + col0;
;                 const f32x4 g0 = acc[ai][0][m][0], g1 = acc[ai][0][m][1], u0 = acc[ai][1][m][0], u1 = acc[ai][1][m][1];
;                 u32x4 w;
;                 w.x = cvt_pk_bf16(silu_f(g0[0]) * u0[0], silu_f(g0[1]) * u0[1]); w.y = cvt_pk_bf16(silu_f(g0[2]) * u0[2], silu_f(g0[3]) * u0[3]);
;                 w.z = cvt_pk_bf16(silu_f(g1[0]) * u1[0], silu_f(g1[1]) * u1[1]); w.w = cvt_pk_bf16(silu_f(g1[2]) * u1[2], silu_f(g1[3]) * u1[3]);
;                 *(u32x4*)rowp = w;
;             }
;     }
	v_add_f32_e32 v155, 1.0, v155
	v_rcp_f32_e32 v154, v154
	v_rcp_f32_e32 v155, v155
	v_cvt_pk_bf16_f32 v153, v151, v153
	v_exp_f32_e64 v158, -v99
	v_mul_f32_e32 v151, v96, v154
	v_mul_f32_e32 v154, v97, v155
	v_exp_f32_e64 v155, -v98
	v_add_f32_e32 v158, 1.0, v158
	v_rcp_f32_e32 v158, v158
	v_mul_f32_e32 v151, v151, v64
	v_add_f32_e32 v155, 1.0, v155
	v_rcp_f32_e32 v155, v155
	v_mul_f32_e32 v154, v154, v65
	v_cvt_pk_bf16_f32 v154, v151, v154
	v_mul_f32_e32 v151, v98, v155
	v_mul_f32_e32 v155, v99, v158
	v_mul_f32_e32 v155, v155, v67
	v_mul_f32_e32 v151, v151, v66
	v_cvt_pk_bf16_f32 v155, v151, v155
	global_store_dwordx4 v[156:157], v[152:155], off
	v_add_u32_e32 v151, 0x80, v150
	v_exp_f32_e64 v154, -v60
	v_exp_f32_e64 v155, -v61
	v_mad_i64_i32 v[152:153], s[2:3], v151, s47, v[142:143]
	v_add_f32_e32 v151, 1.0, v154
	v_add_f32_e32 v154, 1.0, v155
	v_rcp_f32_e32 v154, v154
	v_lshl_add_u64 v[156:157], v[152:153], 0, v[144:145]
	v_exp_f32_e64 v153, -v62
	v_mul_f32_e32 v152, v61, v154
	v_exp_f32_e64 v154, -v63
	v_rcp_f32_e32 v151, v151
	v_add_f32_e32 v153, 1.0, v153
	v_rcp_f32_e32 v153, v153
	v_add_f32_e32 v154, 1.0, v154
	v_rcp_f32_e32 v154, v154
	v_mul_f32_e32 v151, v60, v151
	v_mul_f32_e32 v151, v151, v28
	v_mul_f32_e32 v152, v152, v29
	v_cvt_pk_bf16_f32 v152, v151, v152
	v_mul_f32_e32 v151, v62, v153
	v_mul_f32_e32 v153, v63, v154
	v_exp_f32_e64 v154, -v56
	v_exp_f32_e64 v155, -v57
	v_mul_f32_e32 v151, v151, v30
	v_mul_f32_e32 v153, v153, v31
	v_add_f32_e32 v154, 1.0, v154
	v_add_f32_e32 v155, 1.0, v155
	v_rcp_f32_e32 v154, v154
	v_rcp_f32_e32 v155, v155
	v_cvt_pk_bf16_f32 v153, v151, v153
	v_exp_f32_e64 v158, -v59
	v_mul_f32_e32 v151, v56, v154
	v_mul_f32_e32 v154, v57, v155
	v_exp_f32_e64 v155, -v58
	v_add_f32_e32 v158, 1.0, v158
	v_rcp_f32_e32 v158, v158
	v_mul_f32_e32 v151, v151, v24
	v_add_f32_e32 v155, 1.0, v155
	v_rcp_f32_e32 v155, v155
	v_mul_f32_e32 v154, v154, v25
	v_cvt_pk_bf16_f32 v154, v151, v154
	v_mul_f32_e32 v151, v58, v155
	v_mul_f32_e32 v155, v59, v158
	v_mul_f32_e32 v155, v155, v27
	v_mul_f32_e32 v151, v151, v26
	v_cvt_pk_bf16_f32 v155, v151, v155
	global_store_dwordx4 v[156:157], v[152:155], off
	v_add_u32_e32 v151, 0x90, v150
	v_exp_f32_e64 v154, -v52
	v_exp_f32_e64 v155, -v53
	v_mad_i64_i32 v[152:153], s[2:3], v151, s47, v[142:143]
	v_add_f32_e32 v151, 1.0, v154
	v_add_f32_e32 v154, 1.0, v155
	v_rcp_f32_e32 v154, v154
	v_lshl_add_u64 v[156:157], v[152:153], 0, v[144:145]
	v_exp_f32_e64 v153, -v54
	v_mul_f32_e32 v152, v53, v154
	v_exp_f32_e64 v154, -v55
	v_rcp_f32_e32 v151, v151
	v_add_f32_e32 v153, 1.0, v153
	v_rcp_f32_e32 v153, v153
	v_add_f32_e32 v154, 1.0, v154
	v_rcp_f32_e32 v154, v154
	v_mul_f32_e32 v151, v52, v151
	v_mul_f32_e32 v151, v151, v20
	v_mul_f32_e32 v152, v152, v21
	v_cvt_pk_bf16_f32 v152, v151, v152
	v_mul_f32_e32 v151, v54, v153
	v_mul_f32_e32 v153, v55, v154
	v_exp_f32_e64 v154, -v48
	v_exp_f32_e64 v155, -v49
	v_mul_f32_e32 v151, v151, v22
	v_mul_f32_e32 v153, v153, v23
	v_add_f32_e32 v154, 1.0, v154
	v_add_f32_e32 v155, 1.0, v155
	v_rcp_f32_e32 v154, v154
	v_rcp_f32_e32 v155, v155
	v_cvt_pk_bf16_f32 v153, v151, v153
	v_exp_f32_e64 v158, -v51
	v_mul_f32_e32 v151, v48, v154
	v_mul_f32_e32 v154, v49, v155
	v_exp_f32_e64 v155, -v50
	v_add_f32_e32 v158, 1.0, v158
	v_rcp_f32_e32 v158, v158
	v_mul_f32_e32 v151, v151, v16
	v_add_f32_e32 v155, 1.0, v155
	v_rcp_f32_e32 v155, v155
	v_mul_f32_e32 v154, v154, v17
	v_cvt_pk_bf16_f32 v154, v151, v154
	v_mul_f32_e32 v151, v50, v155
	v_mul_f32_e32 v155, v51, v158
	v_mul_f32_e32 v155, v155, v19
	v_mul_f32_e32 v151, v151, v18
	v_cvt_pk_bf16_f32 v155, v151, v155
	global_store_dwordx4 v[156:157], v[152:155], off
	v_add_u32_e32 v151, 0xa0, v150
	v_exp_f32_e64 v154, -v44
	v_exp_f32_e64 v155, -v45
	v_mad_i64_i32 v[152:153], s[2:3], v151, s47, v[142:143]
	v_add_f32_e32 v151, 1.0, v154
	v_add_f32_e32 v154, 1.0, v155
	v_rcp_f32_e32 v154, v154
	v_lshl_add_u64 v[156:157], v[152:153], 0, v[144:145]
	v_exp_f32_e64 v153, -v46
	v_mul_f32_e32 v152, v45, v154
	v_exp_f32_e64 v154, -v47
	v_rcp_f32_e32 v151, v151
	v_add_f32_e32 v153, 1.0, v153
	v_rcp_f32_e32 v153, v153
	v_add_f32_e32 v154, 1.0, v154
	v_rcp_f32_e32 v154, v154
	v_mul_f32_e32 v151, v44, v151
	v_mul_f32_e32 v151, v151, v12
	v_mul_f32_e32 v152, v152, v13
	v_cvt_pk_bf16_f32 v152, v151, v152
	v_mul_f32_e32 v151, v46, v153
	v_mul_f32_e32 v153, v47, v154
	v_exp_f32_e64 v154, -v40
	v_exp_f32_e64 v155, -v41
	v_mul_f32_e32 v151, v151, v14
	v_mul_f32_e32 v153, v153, v15
	v_add_f32_e32 v154, 1.0, v154
	v_add_f32_e32 v155, 1.0, v155
	v_rcp_f32_e32 v154, v154
	v_rcp_f32_e32 v155, v155
	v_cvt_pk_bf16_f32 v153, v151, v153
	v_exp_f32_e64 v158, -v43
	v_mul_f32_e32 v151, v40, v154
	v_mul_f32_e32 v154, v41, v155
	v_exp_f32_e64 v155, -v42
	v_add_f32_e32 v158, 1.0, v158
	v_rcp_f32_e32 v158, v158
	v_mul_f32_e32 v151, v151, v8
	v_add_f32_e32 v155, 1.0, v155
	v_rcp_f32_e32 v155, v155
	v_mul_f32_e32 v154, v154, v9
	v_cvt_pk_bf16_f32 v154, v151, v154
	v_add_u32_e32 v150, 0xb0, v150
	v_mul_f32_e32 v151, v42, v155
	v_mul_f32_e32 v155, v43, v158
	v_mul_f32_e32 v151, v151, v10
	v_mul_f32_e32 v155, v155, v11
	v_cvt_pk_bf16_f32 v155, v151, v155
	global_store_dwordx4 v[156:157], v[152:155], off
	v_exp_f32_e64 v151, -v36
	v_mad_i64_i32 v[142:143], s[2:3], v150, s47, v[142:143]
	v_exp_f32_e64 v152, -v37
	v_add_f32_e32 v150, 1.0, v151
	v_rcp_f32_e32 v153, v150
	v_add_f32_e32 v150, 1.0, v152
	v_rcp_f32_e32 v152, v150
	v_lshl_add_u64 v[150:151], v[142:143], 0, v[144:145]
	v_exp_f32_e64 v144, -v38
	v_exp_f32_e64 v145, -v39
	v_mul_f32_e32 v142, v36, v153
	v_mul_f32_e32 v143, v37, v152
	v_add_f32_e32 v144, 1.0, v144
	v_add_f32_e32 v145, 1.0, v145
	v_rcp_f32_e32 v144, v144
	v_rcp_f32_e32 v145, v145
	v_mul_f32_e32 v142, v142, v4
	v_mul_f32_e32 v143, v143, v5
	v_cvt_pk_bf16_f32 v142, v142, v143
	v_mul_f32_e32 v143, v38, v144
	v_mul_f32_e32 v144, v39, v145
	v_exp_f32_e64 v145, -v32
	v_exp_f32_e64 v152, -v33
	v_mul_f32_e32 v143, v143, v6
	v_mul_f32_e32 v144, v144, v7
	v_add_f32_e32 v145, 1.0, v145
	v_add_f32_e32 v152, 1.0, v152
	v_rcp_f32_e32 v145, v145
	v_rcp_f32_e32 v152, v152
	v_cvt_pk_bf16_f32 v143, v143, v144
	v_mul_f32_e32 v144, v32, v145
	v_mul_f32_e32 v145, v33, v152
	v_exp_f32_e64 v152, -v34
	v_exp_f32_e64 v153, -v35
	v_mul_f32_e32 v144, v144, v0
	v_mul_f32_e32 v145, v145, v1
	v_add_f32_e32 v152, 1.0, v152
	v_rcp_f32_e32 v152, v152
	v_add_f32_e32 v153, 1.0, v153
	v_rcp_f32_e32 v153, v153
	v_cvt_pk_bf16_f32 v144, v144, v145
	v_mul_f32_e32 v145, v34, v152
	v_mul_f32_e32 v145, v145, v2
	v_mul_f32_e32 v152, v35, v153
	v_mul_f32_e32 v152, v152, v3
	v_cvt_pk_bf16_f32 v145, v145, v152
	global_store_dwordx4 v[150:151], v[142:145], off
	s_cbranch_vccnz .LBB0_318
	s_andn2_b64 vcc, exec, s[10:11]
	s_cbranch_vccnz .LBB0_317
	s_barrier
	s_branch .LBB0_317

; #define LAS __attribute__((address_space(3)))
; __device__ __forceinline__ unsigned pk2(float lo, float hi) { return f2bf(lo) | (f2bf(hi) << 16); }
; __device__ __forceinline__ void transpose_item(const float* W, int ldw, int k0, int nsrc0, bf16_t* WT, int ldt, int drow0, int dk0, LAS float* scr, int lane) {
; #pragma unroll
;     for (int i = 0; i < 8; ++i) { const int kk = 8 * i + (lane >> 3), c4 = lane & 7; const f32x4 v = __builtin_nontemporal_load((const f32x4*)(W + (size_t)(k0 + kk) * ldw + nsrc0 + 4 * c4));
;         scr[kk * 33 + 4 * c4] = v[0]; scr[kk * 33 + 4 * c4 + 1] = v[1]; scr[kk * 33 + 4 * c4 + 2] = v[2]; scr[kk * 33 + 4 * c4 + 3] = v[3]; }
;     asm volatile("s_waitcnt lgkmcnt(0)" ::: "memory");
;     const int c = lane & 7;
; #pragma unroll
;     for (int j = 0; j < 4; ++j) { const int n = (lane >> 3) + 8 * j; const LAS float* s = scr + (8 * c) * 33 + n;
;         u32x4 o; o.x = pk2(s[0 * 33], s[1 * 33]); o.y = pk2(s[2 * 33], s[3 * 33]); o.z = pk2(s[4 * 33], s[5 * 33]); o.w = pk2(s[6 * 33], s[7 * 33]);
;         *(u32x4*)(WT + (size_t)(drow0 + n) * ldt + dk0 + k0 + 8 * c) = o; }
;     asm volatile("s_waitcnt lgkmcnt(0)" ::: "memory");
; }
; __device__ __forceinline__ void weight_transposes(const Args& A, LAS unsigned char* lds, int wk, int nwk, const int tid, const int stage) {
;     const int lane = tid & 63, wave = __builtin_amdgcn_readfirstlane(tid >> 6);
;     unsigned char* ws = A.ws;
;     LAS float* scr = (LAS float*)(lds + wave * 16384);
;     const int gw = wk * 8 + wave, NGW = nwk * 8;
;     constexpr int I_GU = 16 * 88, I_DN = 44 * 32, I_IN = 16 * 72, I_OUT = 12 * 32;
;     const bool ffn2 = stage >= 2;
;     const int n_gu = (stage == 0 || stage == 2) ? 2 * I_GU : 0, n_dn = (stage == 1 || stage == 3) ? I_DN : 0, n_x = stage == 1 ? I_IN : (stage == 4 ? I_OUT : 0);
;     const int nit = n_gu + n_dn + n_x;
;     for (int it = gw; it < nit; it += NGW) {
;         int r = it;
;         if (r < n_gu) {
;             const int up = r / I_GU; r -= up * I_GU; const int kb = r / 88, nb = r % 88, n0 = nb * 32;
;             const float* W = A.in[ffn2 ? (up ? I_F2U : I_F2G) : (up ? I_F1U : I_F1G)];
;             bf16_t* WT = (bf16_t*)(ws + (ffn2 ? WS_WGU2 : WS_WGU1));
;             transpose_item(W, DFF, kb * 64, n0, WT, DM, 256 * (n0 >> 7) + (n0 & 127) + (up ? 128 : 0), 0, scr, lane);
.LBB0_725:
	s_mul_hi_i32 s0, s6, 0x2e8ba2e9
	s_lshr_b32 s2, s0, 31
	s_ashr_i32 s0, s0, 8
	s_add_i32 s0, s0, s2
	s_mulk_i32 s0, 0x580
	s_sub_i32 s0, s6, s0
	s_sext_i32_i16 s2, s0
	s_mulk_i32 s2, 0xba3
	s_lshr_b32 s3, s2, 31
	s_ashr_i32 s2, s2, 18
	s_add_i32 s2, s2, s3
	s_sext_i32_i16 s3, s2
	s_mulk_i32 s2, 0x58
	s_sub_i32 s2, s0, s2
	s_lshl_b32 s0, s3, 6
	s_sext_i32_i16 s3, s2
	s_lshl_b32 s2, s3, 5
	s_lshl_b32 s3, s3, 6
	s_add_i32 s1, s6, 0x57f
	s_and_b32 s9, s3, 0xffffff00
	s_and_b32 s10, s2, 0x60
	s_mov_b32 s98, 0x3f317218
	s_cmpk_lt_u32 s1, 0xaff
	s_cselect_b32 s13, 0, 0x80
	s_cselect_b32 s98, 0x3fb8aa3b, s98
	s_cselect_b32 s1, s85, s87
	s_cselect_b32 s12, s84, s86
	s_ashr_i32 s3, s2, 31
	s_or_b32 s10, s10, s13
	s_lshl_b64 s[2:3], s[2:3], 2
	s_or_b32 s9, s10, s9
	v_or_b32_e32 v29, s0, v4
	s_add_u32 s2, s12, s2
	v_or_b32_e32 v31, s0, v5
	v_or_b32_e32 v33, s0, v6
	v_or_b32_e32 v35, s0, v7
	v_or_b32_e32 v37, s0, v9
	v_or_b32_e32 v39, s0, v10
	v_or_b32_e32 v41, s0, v11
	v_or_b32_e32 v43, s0, v12
	v_mul_i32_i24_e32 v30, 0xb00, v29
	v_or_b32_e32 v46, s9, v4
	v_or_b32_e32 v48, s9, v5
	v_or_b32_e32 v50, s9, v6
	v_or_b32_e32 v52, s9, v7
	s_addc_u32 s3, s1, s3
	v_mul_i32_i24_e32 v32, 0xb00, v31
	v_mul_i32_i24_e32 v34, 0xb00, v33
	v_mul_i32_i24_e32 v36, 0xb00, v35
	v_mul_i32_i24_e32 v38, 0xb00, v37
	v_mul_i32_i24_e32 v40, 0xb00, v39
	v_mul_i32_i24_e32 v42, 0xb00, v41
	v_mul_i32_i24_e32 v44, 0xb00, v43
	v_ashrrev_i32_e32 v31, 31, v30
	s_ashr_i32 s1, s0, 31
	v_ashrrev_i32_e32 v47, 31, v46
	v_ashrrev_i32_e32 v49, 31, v48
	v_ashrrev_i32_e32 v51, 31, v50
	v_ashrrev_i32_e32 v53, 31, v52
	v_lshl_add_u64 v[54:55], s[2:3], 0, v[0:1]
	v_ashrrev_i32_e32 v33, 31, v32
	v_ashrrev_i32_e32 v35, 31, v34
	v_ashrrev_i32_e32 v37, 31, v36
	v_ashrrev_i32_e32 v39, 31, v38
	v_ashrrev_i32_e32 v41, 31, v40
	v_ashrrev_i32_e32 v43, 31, v42
	v_ashrrev_i32_e32 v45, 31, v44
	v_lshl_add_u64 v[56:57], s[0:1], 1, v[2:3]
	v_lshlrev_b64 v[46:47], 11, v[46:47]
	v_lshlrev_b64 v[48:49], 11, v[48:49]
	v_lshlrev_b64 v[50:51], 11, v[50:51]
	v_lshlrev_b64 v[52:53], 11, v[52:53]
	v_lshl_add_u64 v[62:63], v[30:31], 2, v[54:55]
	v_lshl_add_u64 v[64:65], v[32:33], 2, v[54:55]
	v_lshl_add_u64 v[66:67], v[34:35], 2, v[54:55]
	v_lshl_add_u64 v[68:69], v[36:37], 2, v[54:55]
	v_lshl_add_u64 v[70:71], v[38:39], 2, v[54:55]
	v_lshl_add_u64 v[72:73], v[40:41], 2, v[54:55]
	v_lshl_add_u64 v[74:75], v[42:43], 2, v[54:55]
	v_lshl_add_u64 v[76:77], v[44:45], 2, v[54:55]
	v_lshl_add_u64 v[78:79], v[56:57], 0, v[46:47]
	v_lshl_add_u64 v[80:81], v[56:57], 0, v[48:49]
	v_lshl_add_u64 v[82:83], v[56:57], 0, v[50:51]
	v_lshl_add_u64 v[84:85], v[56:57], 0, v[52:53]
	global_load_dwordx4 v[30:33], v[62:63], off nt
	global_load_dwordx4 v[34:37], v[64:65], off nt
	global_load_dwordx4 v[38:41], v[66:67], off nt
	global_load_dwordx4 v[42:45], v[68:69], off nt
	global_load_dwordx4 v[46:49], v[70:71], off nt
	global_load_dwordx4 v[50:53], v[72:73], off nt
	global_load_dwordx4 v[54:57], v[74:75], off nt
	global_load_dwordx4 v[58:61], v[76:77], off nt
	s_add_i32 s6, s6, s4
	s_cmpk_lt_i32 s6, 0xb00
	s_waitcnt vmcnt(0)
	v_mul_f32_e32 v30, s98, v30
	v_mul_f32_e32 v31, s98, v31
	v_mul_f32_e32 v32, s98, v32
	v_mul_f32_e32 v33, s98, v33
	ds_write2_b32 v14, v30, v31 offset1:1
	ds_write2_b32 v14, v32, v33 offset0:2 offset1:3
	v_mul_f32_e32 v34, s98, v34
	v_mul_f32_e32 v35, s98, v35
	v_mul_f32_e32 v36, s98, v36
	v_mul_f32_e32 v37, s98, v37
	ds_write2_b32 v15, v34, v35 offset1:1
	ds_write2_b32 v16, v36, v37 offset1:1
	v_mul_f32_e32 v38, s98, v38
	v_mul_f32_e32 v39, s98, v39
	v_mul_f32_e32 v40, s98, v40
	v_mul_f32_e32 v41, s98, v41
	ds_write2_b32 v17, v38, v39 offset1:1
	ds_write2_b32 v18, v40, v41 offset1:1
	v_mul_f32_e32 v42, s98, v42
	v_mul_f32_e32 v43, s98, v43
	v_mul_f32_e32 v44, s98, v44
	v_mul_f32_e32 v45, s98, v45
	ds_write2_b32 v19, v42, v43 offset1:1
	ds_write2_b32 v20, v44, v45 offset1:1
	v_mul_f32_e32 v46, s98, v46
	v_mul_f32_e32 v47, s98, v47
	v_mul_f32_e32 v48, s98, v48
	v_mul_f32_e32 v49, s98, v49
	ds_write2_b32 v21, v46, v47 offset1:1
	ds_write2_b32 v22, v48, v49 offset1:1
	v_mul_f32_e32 v50, s98, v50
	v_mul_f32_e32 v51, s98, v51
	v_mul_f32_e32 v52, s98, v52
	v_mul_f32_e32 v53, s98, v53
	ds_write2_b32 v23, v50, v51 offset1:1
	ds_write2_b32 v24, v52, v53 offset1:1
	v_mul_f32_e32 v54, s98, v54
	v_mul_f32_e32 v55, s98, v55
	v_mul_f32_e32 v56, s98, v56
	v_mul_f32_e32 v57, s98, v57
	ds_write2_b32 v25, v54, v55 offset1:1
	ds_write2_b32 v26, v56, v57 offset1:1
	v_mul_f32_e32 v58, s98, v58
	v_mul_f32_e32 v59, s98, v59
	v_mul_f32_e32 v60, s98, v60
	v_mul_f32_e32 v61, s98, v61
	ds_write2_b32 v27, v58, v59 offset1:1
	ds_write2_b32 v28, v60, v61 offset1:1
	s_waitcnt lgkmcnt(0)
; #define LAS __attribute__((address_space(3)))
; __device__ __forceinline__ unsigned pk2(float lo, float hi) { return f2bf(lo) | (f2bf(hi) << 16); }
; __device__ __forceinline__ void transpose_item(const float* W, int ldw, int k0, int nsrc0, bf16_t* WT, int ldt, int drow0, int dk0, LAS float* scr, int lane) {
;     ...
;     for (int i = 0; i < 8; ++i) { const int kk = 8 * i + (lane >> 3), c4 = lane & 7; const f32x4 v = __builtin_nontemporal_load((const f32x4*)(W + (size_t)(k0 + kk) * ldw + nsrc0 + 4 * c4));
;         scr[kk * 33 + 4 * c4] = v[0]; scr[kk * 33 + 4 * c4 + 1] = v[1]; scr[kk * 33 + 4 * c4 + 2] = v[2]; scr[kk * 33 + 4 * c4 + 3] = v[3]; }
;     asm volatile("s_waitcnt lgkmcnt(0)" ::: "memory");
;     const int c = lane & 7;
; #pragma unroll
;     for (int j = 0; j < 4; ++j) { const int n = (lane >> 3) + 8 * j; const LAS float* s = scr + (8 * c) * 33 + n;
;         u32x4 o; o.x = pk2(s[0 * 33], s[1 * 33]); o.y = pk2(s[2 * 33], s[3 * 33]); o.z = pk2(s[4 * 33], s[5 * 33]); o.w = pk2(s[6 * 33], s[7 * 33]);
;         *(u32x4*)(WT + (size_t)(drow0 + n) * ldt + dk0 + k0 + 8 * c) = o; }
;     asm volatile("s_waitcnt lgkmcnt(0)" ::: "memory");
	ds_read2_b32 v[30:31], v13 offset0:33 offset1:41
	ds_read2_b32 v[32:33], v13 offset1:8
	ds_read2_b32 v[34:35], v13 offset0:66 offset1:74
	ds_read2_b32 v[36:37], v13 offset0:99 offset1:107
	ds_read2_b32 v[38:39], v13 offset0:132 offset1:140
	ds_read2_b32 v[40:41], v13 offset0:165 offset1:173
	ds_read2_b32 v[42:43], v13 offset0:198 offset1:206
	ds_read2_b32 v[44:45], v13 offset0:231 offset1:239
	ds_read2_b32 v[46:47], v13 offset0:49 offset1:57
	ds_read2_b32 v[48:49], v13 offset0:16 offset1:24
	ds_read2_b32 v[50:51], v13 offset0:82 offset1:90
	ds_read2_b32 v[52:53], v13 offset0:115 offset1:123
	ds_read2_b32 v[54:55], v13 offset0:148 offset1:156
	ds_read2_b32 v[56:57], v13 offset0:181 offset1:189
	ds_read2_b32 v[58:59], v13 offset0:214 offset1:222
	ds_read2_b32 v[60:61], v13 offset0:247 offset1:255
	s_waitcnt lgkmcnt(14)
	v_bfe_u32 v29, v32, 16, 1
	s_waitcnt lgkmcnt(13)
	v_bfe_u32 v63, v34, 16, 1
	s_waitcnt lgkmcnt(12)
	v_bfe_u32 v64, v36, 16, 1
	s_waitcnt lgkmcnt(11)
	v_bfe_u32 v65, v38, 16, 1
	s_waitcnt lgkmcnt(10)
	v_bfe_u32 v66, v40, 16, 1
	s_waitcnt lgkmcnt(9)
	v_bfe_u32 v67, v42, 16, 1
	v_bfe_u32 v62, v30, 16, 1
	s_waitcnt lgkmcnt(8)
	v_bfe_u32 v68, v44, 16, 1
	v_bfe_u32 v69, v33, 16, 1
	v_bfe_u32 v70, v31, 16, 1
	v_bfe_u32 v71, v35, 16, 1
	v_bfe_u32 v72, v37, 16, 1
	v_bfe_u32 v73, v39, 16, 1
	v_bfe_u32 v74, v41, 16, 1
	v_bfe_u32 v75, v43, 16, 1
	v_bfe_u32 v76, v45, 16, 1
	s_waitcnt lgkmcnt(6)
	v_bfe_u32 v77, v48, 16, 1
	s_waitcnt lgkmcnt(5)
	v_bfe_u32 v87, v50, 16, 1
	s_waitcnt lgkmcnt(4)
	v_bfe_u32 v88, v52, 16, 1
	s_waitcnt lgkmcnt(3)
	v_bfe_u32 v89, v54, 16, 1
	s_waitcnt lgkmcnt(2)
	v_bfe_u32 v90, v56, 16, 1
	s_waitcnt lgkmcnt(1)
	v_bfe_u32 v91, v58, 16, 1
	v_bfe_u32 v93, v49, 16, 1
	v_bfe_u32 v95, v51, 16, 1
	v_bfe_u32 v97, v55, 16, 1
	v_bfe_u32 v99, v59, 16, 1
	v_add3_u32 v29, v32, v29, s7
	v_add3_u32 v32, v34, v63, s7
	v_add3_u32 v34, v36, v64, s7
	v_add3_u32 v36, v38, v65, s7
	v_add3_u32 v38, v40, v66, s7
	v_add3_u32 v40, v42, v67, s7
	v_bfe_u32 v86, v46, 16, 1
	s_waitcnt lgkmcnt(0)
	v_bfe_u32 v92, v60, 16, 1
	v_bfe_u32 v94, v47, 16, 1
	v_bfe_u32 v96, v53, 16, 1
	v_bfe_u32 v98, v57, 16, 1
	v_bfe_u32 v100, v61, 16, 1
	v_add3_u32 v30, v30, v62, s7
	v_add3_u32 v42, v44, v68, s7
	v_add3_u32 v33, v33, v69, s7
	v_add3_u32 v44, v31, v70, s7
	v_add3_u32 v31, v35, v71, s7
	v_add3_u32 v35, v37, v72, s7
	v_add3_u32 v37, v39, v73, s7
	v_add3_u32 v39, v41, v74, s7
	v_add3_u32 v41, v43, v75, s7
	v_add3_u32 v43, v45, v76, s7
	v_add3_u32 v45, v48, v77, s7
	v_add3_u32 v48, v50, v87, s7
	v_add3_u32 v50, v52, v88, s7
	v_add3_u32 v52, v54, v89, s7
	v_add3_u32 v54, v56, v90, s7
	v_add3_u32 v56, v58, v91, s7
	v_add3_u32 v49, v49, v93, s7
	v_add3_u32 v51, v51, v95, s7
	v_add3_u32 v55, v55, v97, s7
	v_add3_u32 v59, v59, v99, s7
	v_lshrrev_b32_e32 v29, 16, v29
	v_lshrrev_b32_e32 v32, 16, v32
	v_lshrrev_b32_e32 v36, 16, v36
	v_lshrrev_b32_e32 v40, 16, v40
	v_add3_u32 v46, v46, v86, s7
	v_add3_u32 v58, v60, v92, s7
	v_add3_u32 v47, v47, v94, s7
	v_add3_u32 v53, v53, v96, s7
	v_add3_u32 v57, v57, v98, s7
	v_add3_u32 v60, v61, v100, s7
	v_lshrrev_b32_e32 v61, 16, v33
	v_lshrrev_b32_e32 v62, 16, v31
	v_lshrrev_b32_e32 v37, 16, v37
	v_lshrrev_b32_e32 v41, 16, v41
	v_lshrrev_b32_e32 v45, 16, v45
	v_lshrrev_b32_e32 v48, 16, v48
	v_lshrrev_b32_e32 v52, 16, v52
	v_lshrrev_b32_e32 v56, 16, v56
	v_lshrrev_b32_e32 v49, 16, v49
	v_lshrrev_b32_e32 v51, 16, v51
	v_lshrrev_b32_e32 v55, 16, v55
	v_lshrrev_b32_e32 v59, 16, v59
	v_and_or_b32 v30, v30, s8, v29
	v_and_or_b32 v31, v34, s8, v32
	v_and_or_b32 v32, v38, s8, v36
	v_and_or_b32 v33, v42, s8, v40
	v_and_or_b32 v34, v44, s8, v61
	v_and_or_b32 v35, v35, s8, v62
	v_and_or_b32 v36, v39, s8, v37
	v_and_or_b32 v37, v43, s8, v41
	v_and_or_b32 v38, v46, s8, v45
	v_and_or_b32 v39, v50, s8, v48
	v_and_or_b32 v40, v54, s8, v52
	v_and_or_b32 v41, v58, s8, v56
	v_and_or_b32 v42, v47, s8, v49
	v_and_or_b32 v43, v53, s8, v51
	v_and_or_b32 v44, v57, s8, v55
	v_and_or_b32 v45, v60, s8, v59
	global_store_dwordx4 v[78:79], v[30:33], off
	global_store_dwordx4 v[80:81], v[34:37], off
	global_store_dwordx4 v[82:83], v[38:41], off
	global_store_dwordx4 v[84:85], v[42:45], off
	s_waitcnt lgkmcnt(0)
	s_cbranch_scc1 .LBB0_725

; #define LAS __attribute__((address_space(3)))
; __device__ __forceinline__ unsigned pk2(float lo, float hi) { return f2bf(lo) | (f2bf(hi) << 16); }
; __device__ __forceinline__ void transpose_item(const float* W, int ldw, int k0, int nsrc0, bf16_t* WT, int ldt, int drow0, int dk0, LAS float* scr, int lane) {
; #pragma unroll
;     for (int i = 0; i < 8; ++i) { const int kk = 8 * i + (lane >> 3), c4 = lane & 7; const f32x4 v = __builtin_nontemporal_load((const f32x4*)(W + (size_t)(k0 + kk) * ldw + nsrc0 + 4 * c4));
;         scr[kk * 33 + 4 * c4] = v[0]; scr[kk * 33 + 4 * c4 + 1] = v[1]; scr[kk * 33 + 4 * c4 + 2] = v[2]; scr[kk * 33 + 4 * c4 + 3] = v[3]; }
;     asm volatile("s_waitcnt lgkmcnt(0)" ::: "memory");
;     const int c = lane & 7;
; #pragma unroll
;     for (int j = 0; j < 4; ++j) { const int n = (lane >> 3) + 8 * j; const LAS float* s = scr + (8 * c) * 33 + n;
;         u32x4 o; o.x = pk2(s[0 * 33], s[1 * 33]); o.y = pk2(s[2 * 33], s[3 * 33]); o.z = pk2(s[4 * 33], s[5 * 33]); o.w = pk2(s[6 * 33], s[7 * 33]);
;         *(u32x4*)(WT + (size_t)(drow0 + n) * ldt + dk0 + k0 + 8 * c) = o; }
;     asm volatile("s_waitcnt lgkmcnt(0)" ::: "memory");
; }
; __device__ __forceinline__ void weight_transposes(const Args& A, LAS unsigned char* lds, int wk, int nwk, const int tid, const int stage) {
;     const int lane = tid & 63, wave = __builtin_amdgcn_readfirstlane(tid >> 6);
;     unsigned char* ws = A.ws;
;     LAS float* scr = (LAS float*)(lds + wave * 16384);
;     const int gw = wk * 8 + wave, NGW = nwk * 8;
;     constexpr int I_GU = 16 * 88, I_DN = 44 * 32, I_IN = 16 * 72, I_OUT = 12 * 32;
;     const bool ffn2 = stage >= 2;
;     const int n_gu = (stage == 0 || stage == 2) ? 2 * I_GU : 0, n_dn = (stage == 1 || stage == 3) ? I_DN : 0, n_x = stage == 1 ? I_IN : (stage == 4 ? I_OUT : 0);
;     const int nit = n_gu + n_dn + n_x;
;     for (int it = gw; it < nit; it += NGW) {
;         int r = it;
;         if (r < n_gu) {
;             const int up = r / I_GU; r -= up * I_GU; const int kb = r / 88, nb = r % 88, n0 = nb * 32;
;             const float* W = A.in[ffn2 ? (up ? I_F2U : I_F2G) : (up ? I_F1U : I_F1G)];
;             bf16_t* WT = (bf16_t*)(ws + (ffn2 ? WS_WGU2 : WS_WGU1));
;             transpose_item(W, DFF, kb * 64, n0, WT, DM, 256 * (n0 >> 7) + (n0 & 127) + (up ? 128 : 0), 0, scr, lane);
.LBB0_737:
	s_mul_hi_i32 s0, s4, 0x2e8ba2e9
	s_lshr_b32 s2, s0, 31
	s_ashr_i32 s0, s0, 8
	s_add_i32 s0, s0, s2
	s_mulk_i32 s0, 0x580
	s_sub_i32 s0, s4, s0
	s_sext_i32_i16 s2, s0
	s_mulk_i32 s2, 0xba3
	s_lshr_b32 s3, s2, 31
	s_ashr_i32 s2, s2, 18
	s_add_i32 s2, s2, s3
	s_sext_i32_i16 s3, s2
	s_mulk_i32 s2, 0x58
	s_sub_i32 s2, s0, s2
	s_lshl_b32 s0, s3, 6
	s_sext_i32_i16 s3, s2
	s_lshl_b32 s2, s3, 5
	s_lshl_b32 s3, s3, 6
	s_add_i32 s1, s4, 0x57f
	s_and_b32 s7, s3, 0xffffff00
	s_and_b32 s8, s2, 0x60
	s_mov_b32 s98, 0x3f317218
	s_cmpk_lt_u32 s1, 0xaff
	s_cselect_b32 s11, 0, 0x80
	s_cselect_b32 s98, 0x3fb8aa3b, s98
	s_cselect_b32 s1, s85, s87
	s_cselect_b32 s10, s84, s86
	s_ashr_i32 s3, s2, 31
	s_or_b32 s8, s8, s11
	s_lshl_b64 s[2:3], s[2:3], 2
	s_or_b32 s7, s8, s7
	v_or_b32_e32 v32, s0, v9
	s_add_u32 s2, s10, s2
	v_or_b32_e32 v33, s0, v10
	v_or_b32_e32 v35, s0, v11
	v_or_b32_e32 v37, s0, v12
	v_or_b32_e32 v39, s0, v13
	v_or_b32_e32 v41, s0, v14
	v_or_b32_e32 v43, s0, v15
	v_or_b32_e32 v45, s0, v16
	v_mul_i32_i24_e32 v32, 0xb00, v32
	v_or_b32_e32 v48, s7, v9
	v_or_b32_e32 v50, s7, v10
	v_or_b32_e32 v52, s7, v11
	v_or_b32_e32 v54, s7, v12
	s_addc_u32 s3, s1, s3
	v_mul_i32_i24_e32 v34, 0xb00, v33
	v_mul_i32_i24_e32 v36, 0xb00, v35
	v_mul_i32_i24_e32 v38, 0xb00, v37
	v_mul_i32_i24_e32 v40, 0xb00, v39
	v_mul_i32_i24_e32 v42, 0xb00, v41
	v_mul_i32_i24_e32 v44, 0xb00, v43
	v_mul_i32_i24_e32 v46, 0xb00, v45
	v_ashrrev_i32_e32 v33, 31, v32
	s_ashr_i32 s1, s0, 31
	v_ashrrev_i32_e32 v49, 31, v48
	v_ashrrev_i32_e32 v51, 31, v50
	v_ashrrev_i32_e32 v53, 31, v52
	v_ashrrev_i32_e32 v55, 31, v54
	v_lshl_add_u64 v[56:57], s[2:3], 0, v[0:1]
	v_ashrrev_i32_e32 v35, 31, v34
	v_ashrrev_i32_e32 v37, 31, v36
	v_ashrrev_i32_e32 v39, 31, v38
	v_ashrrev_i32_e32 v41, 31, v40
	v_ashrrev_i32_e32 v43, 31, v42
	v_ashrrev_i32_e32 v45, 31, v44
	v_ashrrev_i32_e32 v47, 31, v46
	v_lshl_add_u64 v[58:59], s[0:1], 1, v[2:3]
	v_lshlrev_b64 v[48:49], 11, v[48:49]
	v_lshlrev_b64 v[50:51], 11, v[50:51]
	v_lshlrev_b64 v[52:53], 11, v[52:53]
	v_lshlrev_b64 v[54:55], 11, v[54:55]
	v_lshl_add_u64 v[64:65], v[32:33], 2, v[56:57]
	v_lshl_add_u64 v[66:67], v[34:35], 2, v[56:57]
	v_lshl_add_u64 v[68:69], v[36:37], 2, v[56:57]
	v_lshl_add_u64 v[70:71], v[38:39], 2, v[56:57]
	v_lshl_add_u64 v[72:73], v[40:41], 2, v[56:57]
	v_lshl_add_u64 v[74:75], v[42:43], 2, v[56:57]
	v_lshl_add_u64 v[76:77], v[44:45], 2, v[56:57]
	v_lshl_add_u64 v[78:79], v[46:47], 2, v[56:57]
	v_lshl_add_u64 v[80:81], v[58:59], 0, v[48:49]
	v_lshl_add_u64 v[82:83], v[58:59], 0, v[50:51]
	v_lshl_add_u64 v[84:85], v[58:59], 0, v[52:53]
	v_lshl_add_u64 v[86:87], v[58:59], 0, v[54:55]
	global_load_dwordx4 v[32:35], v[64:65], off nt
	global_load_dwordx4 v[36:39], v[66:67], off nt
	global_load_dwordx4 v[40:43], v[68:69], off nt
	global_load_dwordx4 v[44:47], v[70:71], off nt
	global_load_dwordx4 v[48:51], v[72:73], off nt
	global_load_dwordx4 v[52:55], v[74:75], off nt
	global_load_dwordx4 v[56:59], v[76:77], off nt
	global_load_dwordx4 v[60:63], v[78:79], off nt
	s_add_i32 s4, s4, s96
	s_cmpk_lt_i32 s4, 0xb00
	s_waitcnt vmcnt(0)
	v_mul_f32_e32 v32, s98, v32
	v_mul_f32_e32 v33, s98, v33
	v_mul_f32_e32 v34, s98, v34
	v_mul_f32_e32 v35, s98, v35
	ds_write2_b32 v17, v32, v33 offset1:1
	ds_write2_b32 v17, v34, v35 offset0:2 offset1:3
	v_mul_f32_e32 v36, s98, v36
	v_mul_f32_e32 v37, s98, v37
	v_mul_f32_e32 v38, s98, v38
	v_mul_f32_e32 v39, s98, v39
	ds_write2_b32 v18, v36, v37 offset1:1
	ds_write2_b32 v19, v38, v39 offset1:1
	v_mul_f32_e32 v40, s98, v40
	v_mul_f32_e32 v41, s98, v41
	v_mul_f32_e32 v42, s98, v42
	v_mul_f32_e32 v43, s98, v43
	ds_write2_b32 v20, v40, v41 offset1:1
	ds_write2_b32 v21, v42, v43 offset1:1
	v_mul_f32_e32 v44, s98, v44
	v_mul_f32_e32 v45, s98, v45
	v_mul_f32_e32 v46, s98, v46
	v_mul_f32_e32 v47, s98, v47
	ds_write2_b32 v22, v44, v45 offset1:1
	ds_write2_b32 v23, v46, v47 offset1:1
	v_mul_f32_e32 v48, s98, v48
	v_mul_f32_e32 v49, s98, v49
	v_mul_f32_e32 v50, s98, v50
	v_mul_f32_e32 v51, s98, v51
	ds_write2_b32 v24, v48, v49 offset1:1
	ds_write2_b32 v25, v50, v51 offset1:1
	v_mul_f32_e32 v52, s98, v52
	v_mul_f32_e32 v53, s98, v53
	v_mul_f32_e32 v54, s98, v54
	v_mul_f32_e32 v55, s98, v55
	ds_write2_b32 v26, v52, v53 offset1:1
	ds_write2_b32 v27, v54, v55 offset1:1
	v_mul_f32_e32 v56, s98, v56
	v_mul_f32_e32 v57, s98, v57
	v_mul_f32_e32 v58, s98, v58
	v_mul_f32_e32 v59, s98, v59
	ds_write2_b32 v28, v56, v57 offset1:1
	ds_write2_b32 v29, v58, v59 offset1:1
	v_mul_f32_e32 v60, s98, v60
	v_mul_f32_e32 v61, s98, v61
	v_mul_f32_e32 v62, s98, v62
	v_mul_f32_e32 v63, s98, v63
	ds_write2_b32 v30, v60, v61 offset1:1
	ds_write2_b32 v31, v62, v63 offset1:1
	s_waitcnt lgkmcnt(0)
; #define LAS __attribute__((address_space(3)))
; __device__ __forceinline__ unsigned pk2(float lo, float hi) { return f2bf(lo) | (f2bf(hi) << 16); }
; __device__ __forceinline__ void transpose_item(const float* W, int ldw, int k0, int nsrc0, bf16_t* WT, int ldt, int drow0, int dk0, LAS float* scr, int lane) {
;     ...
;     for (int i = 0; i < 8; ++i) { const int kk = 8 * i + (lane >> 3), c4 = lane & 7; const f32x4 v = __builtin_nontemporal_load((const f32x4*)(W + (size_t)(k0 + kk) * ldw + nsrc0 + 4 * c4));
;         scr[kk * 33 + 4 * c4] = v[0]; scr[kk * 33 + 4 * c4 + 1] = v[1]; scr[kk * 33 + 4 * c4 + 2] = v[2]; scr[kk * 33 + 4 * c4 + 3] = v[3]; }
;     asm volatile("s_waitcnt lgkmcnt(0)" ::: "memory");
;     const int c = lane & 7;
; #pragma unroll
;     for (int j = 0; j < 4; ++j) { const int n = (lane >> 3) + 8 * j; const LAS float* s = scr + (8 * c) * 33 + n;
;         u32x4 o; o.x = pk2(s[0 * 33], s[1 * 33]); o.y = pk2(s[2 * 33], s[3 * 33]); o.z = pk2(s[4 * 33], s[5 * 33]); o.w = pk2(s[6 * 33], s[7 * 33]);
;         *(u32x4*)(WT + (size_t)(drow0 + n) * ldt + dk0 + k0 + 8 * c) = o; }
;     asm volatile("s_waitcnt lgkmcnt(0)" ::: "memory");
	ds_read2_b32 v[32:33], v7 offset0:33 offset1:41
	ds_read2_b32 v[34:35], v7 offset1:8
	ds_read2_b32 v[36:37], v7 offset0:66 offset1:74
	ds_read2_b32 v[38:39], v7 offset0:99 offset1:107
	ds_read2_b32 v[40:41], v7 offset0:132 offset1:140
	ds_read2_b32 v[42:43], v7 offset0:165 offset1:173
	ds_read2_b32 v[44:45], v7 offset0:198 offset1:206
	ds_read2_b32 v[46:47], v7 offset0:231 offset1:239
	ds_read2_b32 v[48:49], v7 offset0:49 offset1:57
	ds_read2_b32 v[50:51], v7 offset0:16 offset1:24
	ds_read2_b32 v[52:53], v7 offset0:82 offset1:90
	ds_read2_b32 v[54:55], v7 offset0:115 offset1:123
	ds_read2_b32 v[56:57], v7 offset0:148 offset1:156
	ds_read2_b32 v[58:59], v7 offset0:181 offset1:189
	ds_read2_b32 v[60:61], v7 offset0:214 offset1:222
	ds_read2_b32 v[62:63], v7 offset0:247 offset1:255
	s_waitcnt lgkmcnt(14)
	v_bfe_u32 v64, v34, 16, 1
	s_waitcnt lgkmcnt(13)
	v_bfe_u32 v66, v36, 16, 1
	s_waitcnt lgkmcnt(11)
	v_bfe_u32 v68, v40, 16, 1
	s_waitcnt lgkmcnt(9)
	v_bfe_u32 v70, v44, 16, 1
	v_bfe_u32 v65, v32, 16, 1
	v_bfe_u32 v67, v38, 16, 1
	v_bfe_u32 v69, v42, 16, 1
	s_waitcnt lgkmcnt(8)
	v_bfe_u32 v71, v46, 16, 1
	v_bfe_u32 v72, v35, 16, 1
	v_bfe_u32 v73, v33, 16, 1
	v_bfe_u32 v74, v37, 16, 1
	v_bfe_u32 v75, v39, 16, 1
	v_bfe_u32 v76, v41, 16, 1
	v_bfe_u32 v77, v43, 16, 1
	v_bfe_u32 v78, v45, 16, 1
	v_bfe_u32 v79, v47, 16, 1
	s_waitcnt lgkmcnt(6)
	v_bfe_u32 v88, v50, 16, 1
	s_waitcnt lgkmcnt(5)
	v_bfe_u32 v90, v52, 16, 1
	s_waitcnt lgkmcnt(4)
	v_bfe_u32 v91, v54, 16, 1
	s_waitcnt lgkmcnt(3)
	v_bfe_u32 v92, v56, 16, 1
	s_waitcnt lgkmcnt(2)
	v_bfe_u32 v93, v58, 16, 1
	s_waitcnt lgkmcnt(1)
	v_bfe_u32 v94, v60, 16, 1
	v_bfe_u32 v96, v51, 16, 1
	v_bfe_u32 v98, v53, 16, 1
	v_bfe_u32 v100, v57, 16, 1
	v_bfe_u32 v102, v61, 16, 1
	v_add3_u32 v34, v34, v64, s5
	v_add3_u32 v36, v36, v66, s5
	v_add3_u32 v40, v40, v68, s5
	v_add3_u32 v44, v44, v70, s5
	v_bfe_u32 v89, v48, 16, 1
	s_waitcnt lgkmcnt(0)
	v_bfe_u32 v95, v62, 16, 1
	v_bfe_u32 v97, v49, 16, 1
	v_bfe_u32 v99, v55, 16, 1
	v_bfe_u32 v101, v59, 16, 1
	v_bfe_u32 v103, v63, 16, 1
	v_add3_u32 v32, v32, v65, s5
	v_add3_u32 v38, v38, v67, s5
	v_add3_u32 v42, v42, v69, s5
	v_add3_u32 v46, v46, v71, s5
	v_add3_u32 v35, v35, v72, s5
	v_add3_u32 v64, v33, v73, s5
	v_add3_u32 v33, v37, v74, s5
	v_add3_u32 v37, v39, v75, s5
	v_add3_u32 v39, v41, v76, s5
	v_add3_u32 v41, v43, v77, s5
	v_add3_u32 v43, v45, v78, s5
	v_add3_u32 v45, v47, v79, s5
	v_add3_u32 v47, v50, v88, s5
	v_add3_u32 v50, v52, v90, s5
	v_add3_u32 v52, v54, v91, s5
	v_add3_u32 v54, v56, v92, s5
	v_add3_u32 v56, v58, v93, s5
	v_add3_u32 v58, v60, v94, s5
	v_add3_u32 v51, v51, v96, s5
	v_add3_u32 v53, v53, v98, s5
	v_add3_u32 v57, v57, v100, s5
	v_add3_u32 v61, v61, v102, s5
	v_lshrrev_b32_e32 v34, 16, v34
	v_lshrrev_b32_e32 v36, 16, v36
	v_lshrrev_b32_e32 v40, 16, v40
	v_lshrrev_b32_e32 v44, 16, v44
	v_add3_u32 v48, v48, v89, s5
	v_add3_u32 v60, v62, v95, s5
	v_add3_u32 v49, v49, v97, s5
	v_add3_u32 v55, v55, v99, s5
	v_add3_u32 v59, v59, v101, s5
	v_add3_u32 v62, v63, v103, s5
	v_lshrrev_b32_e32 v63, 16, v35
	v_lshrrev_b32_e32 v65, 16, v33
	v_lshrrev_b32_e32 v39, 16, v39
	v_lshrrev_b32_e32 v43, 16, v43
	v_lshrrev_b32_e32 v47, 16, v47
	v_lshrrev_b32_e32 v50, 16, v50
	v_lshrrev_b32_e32 v54, 16, v54
	v_lshrrev_b32_e32 v58, 16, v58
	v_lshrrev_b32_e32 v51, 16, v51
	v_lshrrev_b32_e32 v53, 16, v53
	v_lshrrev_b32_e32 v57, 16, v57
	v_lshrrev_b32_e32 v61, 16, v61
	v_and_or_b32 v32, v32, s6, v34
	v_and_or_b32 v33, v38, s6, v36
	v_and_or_b32 v34, v42, s6, v40
	v_and_or_b32 v35, v46, s6, v44
	v_and_or_b32 v36, v64, s6, v63
	v_and_or_b32 v37, v37, s6, v65
	v_and_or_b32 v38, v41, s6, v39
	v_and_or_b32 v39, v45, s6, v43
	v_and_or_b32 v40, v48, s6, v47
	v_and_or_b32 v41, v52, s6, v50
	v_and_or_b32 v42, v56, s6, v54
	v_and_or_b32 v43, v60, s6, v58
	v_and_or_b32 v44, v49, s6, v51
	v_and_or_b32 v45, v55, s6, v53
	v_and_or_b32 v46, v59, s6, v57
	v_and_or_b32 v47, v62, s6, v61
	global_store_dwordx4 v[80:81], v[32:35], off
	global_store_dwordx4 v[82:83], v[36:39], off
	global_store_dwordx4 v[84:85], v[40:43], off
	global_store_dwordx4 v[86:87], v[44:47], off
	s_waitcnt lgkmcnt(0)
	s_cbranch_scc1 .LBB0_737

; __device__ __forceinline__ unsigned cvt_pk_bf16(float lo, float hi) { unsigned r; asm volatile("v_cvt_pk_bf16_f32 %0, %1, %2" : "=v"(r) : "v"(lo), "v"(hi)); return r; }
; __device__ __forceinline__ float silu_f(float g) { return g * __builtin_amdgcn_rcpf(1.0f + __builtin_amdgcn_exp2f(-1.4426950408889634f * g)); }
;     __device__ __forceinline__ void operator()(const f32x4 (&acc)[2][2][4][2], const Unit& u, int wr, int wc, int fr, int fq) const {
;         const int row0 = u.pm * BM + wr * 64 + fr, col0 = u.pn * 128 + wc * 32 + 8 * fq;
; #pragma unroll
;         for (int ai = 0; ai < 2; ++ai)
; #pragma unroll
;             for (int m = 0; m < 4; ++m) {
;                 bf16_t* rowp = H + (size_t)(row0 + ai * HALF + m * 16) * DFF + col0;
;                 const f32x4 g0 = acc[ai][0][m][0], g1 = acc[ai][0][m][1], u0 = acc[ai][1][m][0], u1 = acc[ai][1][m][1];
;                 u32x4 w;
;                 w.x = cvt_pk_bf16(silu_f(g0[0]) * u0[0], silu_f(g0[1]) * u0[1]); w.y = cvt_pk_bf16(silu_f(g0[2]) * u0[2], silu_f(g0[3]) * u0[3]);
;                 w.z = cvt_pk_bf16(silu_f(g1[0]) * u1[0], silu_f(g1[1]) * u1[1]); w.w = cvt_pk_bf16(silu_f(g1[2]) * u1[2], silu_f(g1[3]) * u1[3]);
;                 *(u32x4*)rowp = w;
;             }
;     }
.LBB0_1274:
	v_exp_f32_e64 v154, -v125
	v_lshl_or_b32 v144, s42, 7, v148
	v_lshl_add_u32 v150, s6, 8, v146
	v_ashrrev_i32_e32 v145, 31, v144
	v_add_f32_e32 v154, 1.0, v154
	v_rcp_f32_e32 v154, v154
	v_mov_b64_e32 v[142:143], s[16:17]
	v_mad_i64_i32 v[152:153], s[2:3], v150, s47, v[142:143]
	v_exp_f32_e64 v151, -v124
	v_lshlrev_b64 v[144:145], 1, v[144:145]
	v_lshl_add_u64 v[156:157], v[152:153], 0, v[144:145]
	v_mul_f32_e32 v152, v125, v154
	v_exp_f32_e64 v153, -v126
	v_exp_f32_e64 v154, -v127
	v_add_f32_e32 v151, 1.0, v151
	v_rcp_f32_e32 v151, v151
	v_add_f32_e32 v153, 1.0, v153
	v_add_f32_e32 v154, 1.0, v154
	v_rcp_f32_e32 v153, v153
	v_rcp_f32_e32 v154, v154
	v_mul_f32_e32 v151, v124, v151
	v_mul_f32_e32 v151, v151, v92
	v_mul_f32_e32 v152, v152, v93
	v_cvt_pk_bf16_f32 v152, v151, v152
	v_mul_f32_e32 v151, v126, v153
	v_mul_f32_e32 v153, v127, v154
	v_exp_f32_e64 v154, -v120
	v_exp_f32_e64 v155, -v121
	v_mul_f32_e32 v151, v151, v94
	v_mul_f32_e32 v153, v153, v95
	v_add_f32_e32 v154, 1.0, v154
	v_add_f32_e32 v155, 1.0, v155
	v_rcp_f32_e32 v154, v154
	v_rcp_f32_e32 v155, v155
	v_cvt_pk_bf16_f32 v153, v151, v153
	v_mul_f32_e32 v151, v120, v154
	v_mul_f32_e32 v154, v121, v155
	v_exp_f32_e64 v155, -v122
	v_exp_f32_e64 v158, -v123
	v_mul_f32_e32 v151, v151, v88
	v_mul_f32_e32 v154, v154, v89
	v_add_f32_e32 v155, 1.0, v155
	v_add_f32_e32 v158, 1.0, v158
	v_rcp_f32_e32 v155, v155
	v_rcp_f32_e32 v158, v158
	v_cvt_pk_bf16_f32 v154, v151, v154
	s_add_u32 s36, s27, 0xffffff00
	v_mul_f32_e32 v151, v122, v155
	v_mul_f32_e32 v155, v123, v158
	v_mul_f32_e32 v155, v155, v91
	v_mul_f32_e32 v151, v151, v90
	v_cvt_pk_bf16_f32 v155, v151, v155
	global_store_dwordx4 v[156:157], v[152:155], off
	v_or_b32_e32 v151, 16, v150
	v_exp_f32_e64 v154, -v116
	v_exp_f32_e64 v155, -v117
	v_mad_i64_i32 v[152:153], s[2:3], v151, s47, v[142:143]
	v_add_f32_e32 v151, 1.0, v154
	v_add_f32_e32 v154, 1.0, v155
	v_rcp_f32_e32 v154, v154
	v_lshl_add_u64 v[156:157], v[152:153], 0, v[144:145]
	v_exp_f32_e64 v153, -v118
	v_mul_f32_e32 v152, v117, v154
	v_exp_f32_e64 v154, -v119
	v_rcp_f32_e32 v151, v151
	v_add_f32_e32 v153, 1.0, v153
	v_rcp_f32_e32 v153, v153
	v_add_f32_e32 v154, 1.0, v154
	v_rcp_f32_e32 v154, v154
	v_mul_f32_e32 v151, v116, v151
	v_mul_f32_e32 v151, v151, v84
	v_mul_f32_e32 v152, v152, v85
	v_cvt_pk_bf16_f32 v152, v151, v152
	v_mul_f32_e32 v151, v118, v153
	v_mul_f32_e32 v153, v119, v154
	v_exp_f32_e64 v154, -v112
	v_exp_f32_e64 v155, -v113
	v_mul_f32_e32 v151, v151, v86
	v_mul_f32_e32 v153, v153, v87
	v_add_f32_e32 v154, 1.0, v154
	v_add_f32_e32 v155, 1.0, v155
	v_rcp_f32_e32 v154, v154
	v_rcp_f32_e32 v155, v155
	v_cvt_pk_bf16_f32 v153, v151, v153
	v_exp_f32_e64 v158, -v115
	v_mul_f32_e32 v151, v112, v154
	v_mul_f32_e32 v154, v113, v155
	v_exp_f32_e64 v155, -v114
	v_add_f32_e32 v158, 1.0, v158
	v_rcp_f32_e32 v158, v158
	v_mul_f32_e32 v151, v151, v80
	v_add_f32_e32 v155, 1.0, v155
	v_rcp_f32_e32 v155, v155
	v_mul_f32_e32 v154, v154, v81
	v_cvt_pk_bf16_f32 v154, v151, v154
	s_addc_u32 s37, s51, -1
	v_mul_f32_e32 v151, v114, v155
	v_mul_f32_e32 v155, v115, v158
	v_mul_f32_e32 v155, v155, v83
	v_mul_f32_e32 v151, v151, v82
	v_cvt_pk_bf16_f32 v155, v151, v155
	global_store_dwordx4 v[156:157], v[152:155], off
	v_or_b32_e32 v151, 32, v150
	v_exp_f32_e64 v154, -v108
	v_exp_f32_e64 v155, -v109
	v_mad_i64_i32 v[152:153], s[2:3], v151, s47, v[142:143]
	v_add_f32_e32 v151, 1.0, v154
	v_add_f32_e32 v154, 1.0, v155
	v_rcp_f32_e32 v154, v154
	v_lshl_add_u64 v[156:157], v[152:153], 0, v[144:145]
	v_exp_f32_e64 v153, -v110
	v_mul_f32_e32 v152, v109, v154
	v_exp_f32_e64 v154, -v111
	v_rcp_f32_e32 v151, v151
	v_add_f32_e32 v153, 1.0, v153
	v_rcp_f32_e32 v153, v153
	v_add_f32_e32 v154, 1.0, v154
	v_rcp_f32_e32 v154, v154
	v_mul_f32_e32 v151, v108, v151
	v_mul_f32_e32 v151, v151, v76
	v_mul_f32_e32 v152, v152, v77
	v_cvt_pk_bf16_f32 v152, v151, v152
	v_mul_f32_e32 v151, v110, v153
	v_mul_f32_e32 v153, v111, v154
	v_exp_f32_e64 v154, -v104
	v_exp_f32_e64 v155, -v105
	v_mul_f32_e32 v151, v151, v78
	v_mul_f32_e32 v153, v153, v79
	v_add_f32_e32 v154, 1.0, v154
	v_add_f32_e32 v155, 1.0, v155
	v_rcp_f32_e32 v154, v154
	v_rcp_f32_e32 v155, v155
	v_cvt_pk_bf16_f32 v153, v151, v153
	v_exp_f32_e64 v158, -v107
	v_mul_f32_e32 v151, v104, v154
	v_mul_f32_e32 v154, v105, v155
	v_exp_f32_e64 v155, -v106
	v_add_f32_e32 v158, 1.0, v158
	v_rcp_f32_e32 v158, v158
	v_mul_f32_e32 v151, v151, v72
	v_add_f32_e32 v155, 1.0, v155
	v_rcp_f32_e32 v155, v155
	v_mul_f32_e32 v154, v154, v73
	v_cvt_pk_bf16_f32 v154, v151, v154
	s_andn2_b64 vcc, exec, s[38:39]
	v_mul_f32_e32 v151, v106, v155
	v_mul_f32_e32 v155, v107, v158
	v_mul_f32_e32 v155, v155, v75
	v_mul_f32_e32 v151, v151, v74
	v_cvt_pk_bf16_f32 v155, v151, v155
	global_store_dwordx4 v[156:157], v[152:155], off
	v_or_b32_e32 v151, 48, v150
	v_exp_f32_e64 v154, -v100
	v_exp_f32_e64 v155, -v101
	v_mad_i64_i32 v[152:153], s[2:3], v151, s47, v[142:143]
	v_add_f32_e32 v151, 1.0, v154
	v_add_f32_e32 v154, 1.0, v155
	v_rcp_f32_e32 v154, v154
	v_lshl_add_u64 v[156:157], v[152:153], 0, v[144:145]
	v_exp_f32_e64 v153, -v102
	v_mul_f32_e32 v152, v101, v154
	v_exp_f32_e64 v154, -v103
	v_rcp_f32_e32 v151, v151
	v_add_f32_e32 v153, 1.0, v153
	v_rcp_f32_e32 v153, v153
	v_add_f32_e32 v154, 1.0, v154
	v_rcp_f32_e32 v154, v154
	v_mul_f32_e32 v151, v100, v151
	v_mul_f32_e32 v151, v151, v68
	v_mul_f32_e32 v152, v152, v69
	v_cvt_pk_bf16_f32 v152, v151, v152
	v_mul_f32_e32 v151, v102, v153
	v_mul_f32_e32 v153, v103, v154
	v_exp_f32_e64 v154, -v96
	v_exp_f32_e64 v155, -v97
	v_mul_f32_e32 v151, v151, v70
	v_mul_f32_e32 v153, v153, v71
	v_add_f32_e32 v154, 1.0, v154
; __device__ __forceinline__ unsigned cvt_pk_bf16(float lo, float hi) { unsigned r; asm volatile("v_cvt_pk_bf16_f32 %0, %1, %2" : "=v"(r) : "v"(lo), "v"(hi)); return r; }
; __device__ __forceinline__ float silu_f(float g) { return g * __builtin_amdgcn_rcpf(1.0f + __builtin_amdgcn_exp2f(-1.4426950408889634f * g)); }
;     __device__ __forceinline__ void operator()(const f32x4 (&acc)[2][2][4][2], const Unit& u, int wr, int wc, int fr, int fq) const {
;         const int row0 = u.pm * BM + wr * 64 + fr, col0 = u.pn * 128 + wc * 32 + 8 * fq;
; #pragma unroll
;         for (int ai = 0; ai < 2; ++ai)
; #pragma unroll
;             for (int m = 0; m < 4; ++m) {
;                 bf16_t* rowp = H + (size_t)(row0 + ai * HALF + m * 16) * DFF + col0;
;                 const f32x4 g0 = acc[ai][0][m][0], g1 = acc[ai][0][m][1], u0 = acc[ai][1][m][0], u1 = acc[ai][1][m][1];
;                 u32x4 w;
;                 w.x = cvt_pk_bf16(silu_f(g0[0]) * u0[0], silu_f(g0[1]) * u0[1]); w.y = cvt_pk_bf16(silu_f(g0[2]) * u0[2], silu_f(g0[3]) * u0[3]);
;                 w.z = cvt_pk_bf16(silu_f(g1[0]) * u1[0], silu_f(g1[1]) * u1[1]); w.w = cvt_pk_bf16(silu_f(g1[2]) * u1[2], silu_f(g1[3]) * u1[3]);
;                 *(u32x4*)rowp = w;
;             }
;     }
	v_add_f32_e32 v155, 1.0, v155
	v_rcp_f32_e32 v154, v154
	v_rcp_f32_e32 v155, v155
	v_cvt_pk_bf16_f32 v153, v151, v153
	v_exp_f32_e64 v158, -v99
	v_mul_f32_e32 v151, v96, v154
	v_mul_f32_e32 v154, v97, v155
	v_exp_f32_e64 v155, -v98
	v_add_f32_e32 v158, 1.0, v158
	v_rcp_f32_e32 v158, v158
	v_mul_f32_e32 v151, v151, v64
	v_add_f32_e32 v155, 1.0, v155
	v_rcp_f32_e32 v155, v155
	v_mul_f32_e32 v154, v154, v65
	v_cvt_pk_bf16_f32 v154, v151, v154
	v_mul_f32_e32 v151, v98, v155
	v_mul_f32_e32 v155, v99, v158
	v_mul_f32_e32 v155, v155, v67
	v_mul_f32_e32 v151, v151, v66
	v_cvt_pk_bf16_f32 v155, v151, v155
	global_store_dwordx4 v[156:157], v[152:155], off
	v_add_u32_e32 v151, 0x80, v150
	v_exp_f32_e64 v154, -v60
	v_exp_f32_e64 v155, -v61
	v_mad_i64_i32 v[152:153], s[2:3], v151, s47, v[142:143]
	v_add_f32_e32 v151, 1.0, v154
	v_add_f32_e32 v154, 1.0, v155
	v_rcp_f32_e32 v154, v154
	v_lshl_add_u64 v[156:157], v[152:153], 0, v[144:145]
	v_exp_f32_e64 v153, -v62
	v_mul_f32_e32 v152, v61, v154
	v_exp_f32_e64 v154, -v63
	v_rcp_f32_e32 v151, v151
	v_add_f32_e32 v153, 1.0, v153
	v_rcp_f32_e32 v153, v153
	v_add_f32_e32 v154, 1.0, v154
	v_rcp_f32_e32 v154, v154
	v_mul_f32_e32 v151, v60, v151
	v_mul_f32_e32 v151, v151, v28
	v_mul_f32_e32 v152, v152, v29
	v_cvt_pk_bf16_f32 v152, v151, v152
	v_mul_f32_e32 v151, v62, v153
	v_mul_f32_e32 v153, v63, v154
	v_exp_f32_e64 v154, -v56
	v_exp_f32_e64 v155, -v57
	v_mul_f32_e32 v151, v151, v30
	v_mul_f32_e32 v153, v153, v31
	v_add_f32_e32 v154, 1.0, v154
	v_add_f32_e32 v155, 1.0, v155
	v_rcp_f32_e32 v154, v154
	v_rcp_f32_e32 v155, v155
	v_cvt_pk_bf16_f32 v153, v151, v153
	v_exp_f32_e64 v158, -v59
	v_mul_f32_e32 v151, v56, v154
	v_mul_f32_e32 v154, v57, v155
	v_exp_f32_e64 v155, -v58
	v_add_f32_e32 v158, 1.0, v158
	v_rcp_f32_e32 v158, v158
	v_mul_f32_e32 v151, v151, v24
	v_add_f32_e32 v155, 1.0, v155
	v_rcp_f32_e32 v155, v155
	v_mul_f32_e32 v154, v154, v25
	v_cvt_pk_bf16_f32 v154, v151, v154
	v_mul_f32_e32 v151, v58, v155
	v_mul_f32_e32 v155, v59, v158
	v_mul_f32_e32 v155, v155, v27
	v_mul_f32_e32 v151, v151, v26
	v_cvt_pk_bf16_f32 v155, v151, v155
	global_store_dwordx4 v[156:157], v[152:155], off
	v_add_u32_e32 v151, 0x90, v150
	v_exp_f32_e64 v154, -v52
	v_exp_f32_e64 v155, -v53
	v_mad_i64_i32 v[152:153], s[2:3], v151, s47, v[142:143]
	v_add_f32_e32 v151, 1.0, v154
	v_add_f32_e32 v154, 1.0, v155
	v_rcp_f32_e32 v154, v154
	v_lshl_add_u64 v[156:157], v[152:153], 0, v[144:145]
	v_exp_f32_e64 v153, -v54
	v_mul_f32_e32 v152, v53, v154
	v_exp_f32_e64 v154, -v55
	v_rcp_f32_e32 v151, v151
	v_add_f32_e32 v153, 1.0, v153
	v_rcp_f32_e32 v153, v153
	v_add_f32_e32 v154, 1.0, v154
	v_rcp_f32_e32 v154, v154
	v_mul_f32_e32 v151, v52, v151
	v_mul_f32_e32 v151, v151, v20
	v_mul_f32_e32 v152, v152, v21
	v_cvt_pk_bf16_f32 v152, v151, v152
	v_mul_f32_e32 v151, v54, v153
	v_mul_f32_e32 v153, v55, v154
	v_exp_f32_e64 v154, -v48
	v_exp_f32_e64 v155, -v49
	v_mul_f32_e32 v151, v151, v22
	v_mul_f32_e32 v153, v153, v23
	v_add_f32_e32 v154, 1.0, v154
	v_add_f32_e32 v155, 1.0, v155
	v_rcp_f32_e32 v154, v154
	v_rcp_f32_e32 v155, v155
	v_cvt_pk_bf16_f32 v153, v151, v153
	v_exp_f32_e64 v158, -v51
	v_mul_f32_e32 v151, v48, v154
	v_mul_f32_e32 v154, v49, v155
	v_exp_f32_e64 v155, -v50
	v_add_f32_e32 v158, 1.0, v158
	v_rcp_f32_e32 v158, v158
	v_mul_f32_e32 v151, v151, v16
	v_add_f32_e32 v155, 1.0, v155
	v_rcp_f32_e32 v155, v155
	v_mul_f32_e32 v154, v154, v17
	v_cvt_pk_bf16_f32 v154, v151, v154
	v_mul_f32_e32 v151, v50, v155
	v_mul_f32_e32 v155, v51, v158
	v_mul_f32_e32 v155, v155, v19
	v_mul_f32_e32 v151, v151, v18
	v_cvt_pk_bf16_f32 v155, v151, v155
	global_store_dwordx4 v[156:157], v[152:155], off
	v_add_u32_e32 v151, 0xa0, v150
	v_exp_f32_e64 v154, -v44
	v_exp_f32_e64 v155, -v45
	v_mad_i64_i32 v[152:153], s[2:3], v151, s47, v[142:143]
	v_add_f32_e32 v151, 1.0, v154
	v_add_f32_e32 v154, 1.0, v155
	v_rcp_f32_e32 v154, v154
	v_lshl_add_u64 v[156:157], v[152:153], 0, v[144:145]
	v_exp_f32_e64 v153, -v46
	v_mul_f32_e32 v152, v45, v154
	v_exp_f32_e64 v154, -v47
	v_rcp_f32_e32 v151, v151
	v_add_f32_e32 v153, 1.0, v153
	v_rcp_f32_e32 v153, v153
	v_add_f32_e32 v154, 1.0, v154
	v_rcp_f32_e32 v154, v154
	v_mul_f32_e32 v151, v44, v151
	v_mul_f32_e32 v151, v151, v12
	v_mul_f32_e32 v152, v152, v13
	v_cvt_pk_bf16_f32 v152, v151, v152
	v_mul_f32_e32 v151, v46, v153
	v_mul_f32_e32 v153, v47, v154
	v_exp_f32_e64 v154, -v40
	v_exp_f32_e64 v155, -v41
	v_mul_f32_e32 v151, v151, v14
	v_mul_f32_e32 v153, v153, v15
	v_add_f32_e32 v154, 1.0, v154
	v_add_f32_e32 v155, 1.0, v155
	v_rcp_f32_e32 v154, v154
	v_rcp_f32_e32 v155, v155
	v_cvt_pk_bf16_f32 v153, v151, v153
	v_exp_f32_e64 v158, -v43
	v_mul_f32_e32 v151, v40, v154
	v_mul_f32_e32 v154, v41, v155
	v_exp_f32_e64 v155, -v42
	v_add_f32_e32 v158, 1.0, v158
	v_rcp_f32_e32 v158, v158
	v_mul_f32_e32 v151, v151, v8
	v_add_f32_e32 v155, 1.0, v155
	v_rcp_f32_e32 v155, v155
	v_mul_f32_e32 v154, v154, v9
	v_cvt_pk_bf16_f32 v154, v151, v154
	v_add_u32_e32 v150, 0xb0, v150
	v_mul_f32_e32 v151, v42, v155
	v_mul_f32_e32 v155, v43, v158
	v_mul_f32_e32 v151, v151, v10
	v_mul_f32_e32 v155, v155, v11
	v_cvt_pk_bf16_f32 v155, v151, v155
	global_store_dwordx4 v[156:157], v[152:155], off
	v_exp_f32_e64 v151, -v36
	v_mad_i64_i32 v[142:143], s[2:3], v150, s47, v[142:143]
	v_exp_f32_e64 v152, -v37
	v_add_f32_e32 v150, 1.0, v151
	v_rcp_f32_e32 v153, v150
	v_add_f32_e32 v150, 1.0, v152
	v_rcp_f32_e32 v152, v150
	v_lshl_add_u64 v[150:151], v[142:143], 0, v[144:145]
	v_exp_f32_e64 v144, -v38
	v_exp_f32_e64 v145, -v39
	v_mul_f32_e32 v142, v36, v153
	v_mul_f32_e32 v143, v37, v152
	v_add_f32_e32 v144, 1.0, v144
	v_add_f32_e32 v145, 1.0, v145
	v_rcp_f32_e32 v144, v144
	v_rcp_f32_e32 v145, v145
	v_mul_f32_e32 v142, v142, v4
	v_mul_f32_e32 v143, v143, v5
	v_cvt_pk_bf16_f32 v142, v142, v143
	v_mul_f32_e32 v143, v38, v144
	v_mul_f32_e32 v144, v39, v145
	v_exp_f32_e64 v145, -v32
	v_exp_f32_e64 v152, -v33
	v_mul_f32_e32 v143, v143, v6
	v_mul_f32_e32 v144, v144, v7
	v_add_f32_e32 v145, 1.0, v145
	v_add_f32_e32 v152, 1.0, v152
	v_rcp_f32_e32 v145, v145
	v_rcp_f32_e32 v152, v152
	v_cvt_pk_bf16_f32 v143, v143, v144
	v_mul_f32_e32 v144, v32, v145
	v_mul_f32_e32 v145, v33, v152
	v_exp_f32_e64 v152, -v34
	v_exp_f32_e64 v153, -v35
	v_mul_f32_e32 v144, v144, v0
	v_mul_f32_e32 v145, v145, v1
	v_add_f32_e32 v152, 1.0, v152
	v_rcp_f32_e32 v152, v152
	v_add_f32_e32 v153, 1.0, v153
	v_rcp_f32_e32 v153, v153
	v_cvt_pk_bf16_f32 v144, v144, v145
	v_mul_f32_e32 v145, v34, v152
	v_mul_f32_e32 v145, v145, v2
	v_mul_f32_e32 v152, v35, v153
	v_mul_f32_e32 v152, v152, v3
	v_cvt_pk_bf16_f32 v145, v145, v152
	global_store_dwordx4 v[150:151], v[142:145], off
	s_cbranch_vccnz .LBB0_1265
	s_andn2_b64 vcc, exec, s[10:11]
	s_cbranch_vccnz .LBB0_1264
	s_barrier
	s_branch .LBB0_1264
